# K-loop: drop the compiler's redundant s_waitcnt lgkmcnt(0) between the opening barrier and the first MFMA (the load segment already waited before the barrier)
# speedup vs baseline: 1.0000x; 1.0000x over previous
; #define PG8_STAGE(bufoff, gbase, voff) do { _Pragma("unroll") for (int _i = 0; _i < 2; ++_i) \
;         __builtin_amdgcn_global_load_lds((const unsigned*)((const char*)(gbase) + (voff)[_i]), (PG8_LAS unsigned*)(lds + (bufoff) + ldsw + _i * 8192), 16, 0, 0); } while (0)
; #define PG8_LDA(dst, b, h) do { _Pragma("unroll") for (int m = 0; m < 4; ++m) _Pragma("unroll") for (int k = 0; k < 2; ++k) dst[m][k] = *(const PG8_LAS bf16x8*)(lds + PG8_SA(b, h) + aoff + m * 2048 + k * 1024); } while (0)
; #define PG8_LDB(dst, b, h) do { _Pragma("unroll") for (int n = 0; n < 2; ++n) _Pragma("unroll") for (int k = 0; k < 2; ++k) dst[n][k] = *(const PG8_LAS bf16x8*)(lds + PG8_SB(b, h) + boff + n * 2048 + k * 1024); } while (0)
; #define PG8_MMA(ai, bj, At, Bt) do { __builtin_amdgcn_s_setprio(1); _Pragma("unroll") for (int m = 0; m < 4; ++m) _Pragma("unroll") for (int n = 0; n < 2; ++n) _Pragma("unroll") for (int k = 0; k < 2; ++k) \
;         acc[ai][bj][m][n] = __builtin_amdgcn_mfma_f32_16x16x32_bf16(Bt[n][k], At[m][k], acc[ai][bj][m][n], 0, 0, 0); __builtin_amdgcn_s_setprio(0); } while (0)
; #define PG8_WAIT_V(n) asm volatile("s_waitcnt vmcnt(" #n ")" ::: "memory")
; #define PG8_WAIT_L(n) asm volatile("s_waitcnt lgkmcnt(" #n ")" ::: "memory")
; #define PG8_BAR __builtin_amdgcn_s_barrier()
; #define PG8_SCHED __builtin_amdgcn_sched_barrier(0)
; template <class Epi, class Sched, bool ALIGN_EPI = false, bool SP2 = false>
; __device__ __forceinline__ void gemm_phase(PG8_LAS unsigned char* lds, const Gemm g, const Sched& S, const Epi& E) {
;     ...
;             const bool last = (t == nt - 2);
;             const char* a1 = cA + (size_t)(t + 1) * kstep;
;             const char* a2 = last ? nA : cA + (size_t)(t + 2) * kstep; const char* b2 = last ? nB : cB + (size_t)(t + 2) * kstep;
;             const char* a3 = a2 + kstep; const char* b3 = b2 + kstep;
;             if (last && has_next) S.a_ready(nxt);
;             if constexpr (SP2) {
;             PG8_LDB(B0, 0, 0); PG8_LDB(B1, 0, 1); PG8_SCHED; PG8_LDA(At, 0, 0); PG8_STAGE(PG8_SA(1, 1), a1 + hstep, voffA);
;             PG8_WAIT_V(8); PG8_WAIT_L(0); PG8_BAR; PG8_MMA(0, 0, At, B0); PG8_MMA(0, 1, At, B1); PG8_BAR; PG8_SCHED;
;             if (full) PG8_LDA(At, 0, 1); PG8_STAGE(PG8_SB(0, 0), b2, voffB); PG8_STAGE(PG8_SB(0, 1), b2 + hstep, voffB); PG8_STAGE(PG8_SA(0, 0), a2, voffA);
.LBB0_292:
	v_add_u32_e32 v0, 0x10000, v223
	ds_read_b128 v[148:151], v0
	ds_read_b128 v[152:155], v0 offset:1024
	ds_read_b128 v[156:159], v0 offset:2048
	ds_read_b128 v[160:163], v0 offset:3072
	v_add_u32_e32 v0, 0x14000, v223
	ds_read_b128 v[132:135], v0
	ds_read_b128 v[136:139], v0 offset:1024
	ds_read_b128 v[140:143], v0 offset:2048
	ds_read_b128 v[144:147], v0 offset:3072
	v_lshl_add_u64 v[2:3], s[36:37], 0, v[204:205]
	s_add_i32 m0, s31, 0xc000
	ds_read_b128 v[176:179], v224
	ds_read_b128 v[192:195], v224 offset:1024
	ds_read_b128 v[172:175], v224 offset:2048
	ds_read_b128 v[188:191], v224 offset:3072
	ds_read_b128 v[168:171], v224 offset:4096
	ds_read_b128 v[184:187], v224 offset:5120
	ds_read_b128 v[164:167], v224 offset:6144
	ds_read_b128 v[180:183], v224 offset:7168
	global_load_lds_dwordx4 v[2:3], off
	v_lshl_add_u64 v[2:3], s[36:37], 0, v[206:207]
	s_add_i32 m0, s31, 0xe000
	s_nop 0
	global_load_lds_dwordx4 v[2:3], off
	s_waitcnt vmcnt(8)
	s_waitcnt lgkmcnt(0)
	s_setprio 1
	s_barrier
	v_mfma_f32_16x16x32_bf16 v[128:131], v[148:151], v[176:179], v[128:131]
	v_mfma_f32_16x16x32_bf16 v[124:127], v[156:159], v[176:179], v[124:127]
	v_mfma_f32_16x16x32_bf16 v[112:115], v[148:151], v[172:175], v[112:115]
	v_mfma_f32_16x16x32_bf16 v[108:111], v[156:159], v[172:175], v[108:111]
	v_mfma_f32_16x16x32_bf16 v[96:99], v[148:151], v[168:171], v[96:99]
	v_mfma_f32_16x16x32_bf16 v[92:95], v[156:159], v[168:171], v[92:95]
	v_mfma_f32_16x16x32_bf16 v[80:83], v[148:151], v[164:167], v[80:83]
	v_mfma_f32_16x16x32_bf16 v[76:79], v[156:159], v[164:167], v[76:79]
	v_mfma_f32_16x16x32_bf16 v[128:131], v[152:155], v[192:195], v[128:131]
	v_mfma_f32_16x16x32_bf16 v[124:127], v[160:163], v[192:195], v[124:127]
	v_mfma_f32_16x16x32_bf16 v[112:115], v[152:155], v[188:191], v[112:115]
	v_mfma_f32_16x16x32_bf16 v[108:111], v[160:163], v[188:191], v[108:111]
	v_mfma_f32_16x16x32_bf16 v[96:99], v[152:155], v[184:187], v[96:99]
	v_mfma_f32_16x16x32_bf16 v[92:95], v[160:163], v[184:187], v[92:95]
	v_mfma_f32_16x16x32_bf16 v[80:83], v[152:155], v[180:183], v[80:83]
	v_mfma_f32_16x16x32_bf16 v[76:79], v[160:163], v[180:183], v[76:79]
	v_mfma_f32_16x16x32_bf16 v[120:123], v[132:135], v[176:179], v[120:123]
	v_mfma_f32_16x16x32_bf16 v[116:119], v[140:143], v[176:179], v[116:119]
	v_mfma_f32_16x16x32_bf16 v[104:107], v[132:135], v[172:175], v[104:107]
	v_mfma_f32_16x16x32_bf16 v[100:103], v[140:143], v[172:175], v[100:103]
	v_mfma_f32_16x16x32_bf16 v[88:91], v[132:135], v[168:171], v[88:91]
	v_mfma_f32_16x16x32_bf16 v[84:87], v[140:143], v[168:171], v[84:87]
	v_mfma_f32_16x16x32_bf16 v[72:75], v[132:135], v[164:167], v[72:75]
	v_mfma_f32_16x16x32_bf16 v[68:71], v[140:143], v[164:167], v[68:71]
	v_mfma_f32_16x16x32_bf16 v[120:123], v[136:139], v[192:195], v[120:123]
	v_mfma_f32_16x16x32_bf16 v[116:119], v[144:147], v[192:195], v[116:119]
	v_mfma_f32_16x16x32_bf16 v[104:107], v[136:139], v[188:191], v[104:107]
	v_mfma_f32_16x16x32_bf16 v[100:103], v[144:147], v[188:191], v[100:103]
	v_mfma_f32_16x16x32_bf16 v[88:91], v[136:139], v[184:187], v[88:91]
	v_mfma_f32_16x16x32_bf16 v[84:87], v[144:147], v[184:187], v[84:87]
	v_mfma_f32_16x16x32_bf16 v[72:75], v[136:139], v[180:183], v[72:75]
	v_mfma_f32_16x16x32_bf16 v[68:71], v[144:147], v[180:183], v[68:71]
	s_barrier
	s_setprio 0
	v_cndmask_b32_e64 v0, 0, 1, s[34:35]
	v_cmp_ne_u32_e64 s[4:5], 1, v0
	s_andn2_b64 vcc, exec, s[34:35]
	s_cbranch_vccnz .LBB0_294
	ds_read_b128 v[176:179], v224 offset:16384
	ds_read_b128 v[192:195], v224 offset:17408
	ds_read_b128 v[172:175], v224 offset:18432
	ds_read_b128 v[188:191], v224 offset:19456
	ds_read_b128 v[168:171], v224 offset:20480
	ds_read_b128 v[184:187], v224 offset:21504
	ds_read_b128 v[164:167], v224 offset:22528
	ds_read_b128 v[180:183], v224 offset:23552
.LBB0_294:
	s_add_u32 s38, s36, 0xfffc0080
	s_addc_u32 s39, s37, -1
	s_cmp_eq_u32 s89, 12
	s_cselect_b32 s43, s23, s39
	s_cselect_b32 s42, s81, s38
	s_cselect_b32 s39, s21, s88
	s_cselect_b32 s38, s82, s83
	s_mov_b32 m0, s54
	v_lshl_add_u64 v[2:3], s[38:39], 0, v[198:199]
	s_add_u32 s90, s38, 0x40000
	global_load_lds_dwordx4 v[2:3], off
	v_lshl_add_u64 v[208:209], s[38:39], 0, v[202:203]
	s_mov_b32 m0, s55
	s_addc_u32 s91, s39, 0
	global_load_lds_dwordx4 v[208:209], off
	v_lshl_add_u64 v[210:211], s[90:91], 0, v[198:199]
	s_mov_b32 m0, s56
	v_lshl_add_u64 v[220:221], s[42:43], 0, v[200:201]
	global_load_lds_dwordx4 v[210:211], off
	v_lshl_add_u64 v[210:211], s[90:91], 0, v[202:203]
	s_mov_b32 m0, s57
	s_and_b64 vcc, exec, s[4:5]
	global_load_lds_dwordx4 v[210:211], off
	v_lshl_add_u64 v[210:211], s[42:43], 0, v[196:197]
	s_mov_b32 m0, s31
	s_nop 0
	global_load_lds_dwordx4 v[210:211], off
	s_mov_b32 m0, s58
	s_nop 0
	global_load_lds_dwordx4 v[220:221], off
	s_waitcnt vmcnt(8)
	s_waitcnt lgkmcnt(0)
	s_setprio 1
	s_barrier
	s_cbranch_vccnz .LBB0_296
; #define PG8_STAGE(bufoff, gbase, voff) do { _Pragma("unroll") for (int _i = 0; _i < 2; ++_i) \
;         __builtin_amdgcn_global_load_lds((const unsigned*)((const char*)(gbase) + (voff)[_i]), (PG8_LAS unsigned*)(lds + (bufoff) + ldsw + _i * 8192), 16, 0, 0); } while (0)
; #define PG8_LDA(dst, b, h) do { _Pragma("unroll") for (int m = 0; m < 4; ++m) _Pragma("unroll") for (int k = 0; k < 2; ++k) dst[m][k] = *(const PG8_LAS bf16x8*)(lds + PG8_SA(b, h) + aoff + m * 2048 + k * 1024); } while (0)
; #define PG8_LDB(dst, b, h) do { _Pragma("unroll") for (int n = 0; n < 2; ++n) _Pragma("unroll") for (int k = 0; k < 2; ++k) dst[n][k] = *(const PG8_LAS bf16x8*)(lds + PG8_SB(b, h) + boff + n * 2048 + k * 1024); } while (0)
; #define PG8_MMA(ai, bj, At, Bt) do { __builtin_amdgcn_s_setprio(1); _Pragma("unroll") for (int m = 0; m < 4; ++m) _Pragma("unroll") for (int n = 0; n < 2; ++n) _Pragma("unroll") for (int k = 0; k < 2; ++k) \
;         acc[ai][bj][m][n] = __builtin_amdgcn_mfma_f32_16x16x32_bf16(Bt[n][k], At[m][k], acc[ai][bj][m][n], 0, 0, 0); __builtin_amdgcn_s_setprio(0); } while (0)
; #define PG8_WAIT_V(n) asm volatile("s_waitcnt vmcnt(" #n ")" ::: "memory")
; #define PG8_WAIT_L(n) asm volatile("s_waitcnt lgkmcnt(" #n ")" ::: "memory")
; #define PG8_BAR __builtin_amdgcn_s_barrier()
; #define PG8_SCHED __builtin_amdgcn_sched_barrier(0)
; template <class Epi, class Sched, bool ALIGN_EPI = false, bool SP2 = false>
; __device__ __forceinline__ void gemm_phase(PG8_LAS unsigned char* lds, const Gemm g, const Sched& S, const Epi& E) {
;     ...
;             PG8_WAIT_V(8); PG8_WAIT_L(0); PG8_BAR; if (full) { PG8_MMA(1, 0, At, B0); PG8_MMA(1, 1, At, B1); } PG8_BAR; PG8_SCHED;
;             PG8_LDB(B0, 1, 0); PG8_LDB(B1, 1, 1); PG8_SCHED; PG8_LDA(At, 1, 0); PG8_STAGE(PG8_SA(0, 1), a2 + hstep, voffA);
;             PG8_WAIT_V(8); PG8_WAIT_L(0); PG8_BAR; PG8_MMA(0, 0, At, B0); PG8_MMA(0, 1, At, B1); PG8_BAR; PG8_SCHED;
;             if (full) PG8_LDA(At, 1, 1); PG8_STAGE(PG8_SB(1, 0), b3, voffB); PG8_STAGE(PG8_SB(1, 1), b3 + hstep, voffB); PG8_STAGE(PG8_SA(1, 0), a3, voffA);
	s_setprio 1
	v_mfma_f32_16x16x32_bf16 v[64:67], v[148:151], v[176:179], v[64:67]
	v_mfma_f32_16x16x32_bf16 v[56:59], v[156:159], v[176:179], v[56:59]
	v_mfma_f32_16x16x32_bf16 v[48:51], v[148:151], v[172:175], v[48:51]
	v_mfma_f32_16x16x32_bf16 v[40:43], v[156:159], v[172:175], v[40:43]
	v_mfma_f32_16x16x32_bf16 v[32:35], v[148:151], v[168:171], v[32:35]
	v_mfma_f32_16x16x32_bf16 v[24:27], v[156:159], v[168:171], v[24:27]
	v_mfma_f32_16x16x32_bf16 v[16:19], v[148:151], v[164:167], v[16:19]
	v_mfma_f32_16x16x32_bf16 v[8:11], v[156:159], v[164:167], v[8:11]
	v_mfma_f32_16x16x32_bf16 v[64:67], v[152:155], v[192:195], v[64:67]
	v_mfma_f32_16x16x32_bf16 v[56:59], v[160:163], v[192:195], v[56:59]
	v_mfma_f32_16x16x32_bf16 v[48:51], v[152:155], v[188:191], v[48:51]
	v_mfma_f32_16x16x32_bf16 v[40:43], v[160:163], v[188:191], v[40:43]
	v_mfma_f32_16x16x32_bf16 v[32:35], v[152:155], v[184:187], v[32:35]
	v_mfma_f32_16x16x32_bf16 v[24:27], v[160:163], v[184:187], v[24:27]
	v_mfma_f32_16x16x32_bf16 v[16:19], v[152:155], v[180:183], v[16:19]
	v_mfma_f32_16x16x32_bf16 v[8:11], v[160:163], v[180:183], v[8:11]
	v_mfma_f32_16x16x32_bf16 v[60:63], v[132:135], v[176:179], v[60:63]
	v_mfma_f32_16x16x32_bf16 v[52:55], v[140:143], v[176:179], v[52:55]
	v_mfma_f32_16x16x32_bf16 v[44:47], v[132:135], v[172:175], v[44:47]
	v_mfma_f32_16x16x32_bf16 v[36:39], v[140:143], v[172:175], v[36:39]
	v_mfma_f32_16x16x32_bf16 v[28:31], v[132:135], v[168:171], v[28:31]
	v_mfma_f32_16x16x32_bf16 v[20:23], v[140:143], v[168:171], v[20:23]
	v_mfma_f32_16x16x32_bf16 v[12:15], v[132:135], v[164:167], v[12:15]
	v_mfma_f32_16x16x32_bf16 v[4:7], v[140:143], v[164:167], v[4:7]
	v_mfma_f32_16x16x32_bf16 v[60:63], v[136:139], v[192:195], v[60:63]
	v_mfma_f32_16x16x32_bf16 v[52:55], v[144:147], v[192:195], v[52:55]
	v_mfma_f32_16x16x32_bf16 v[44:47], v[136:139], v[188:191], v[44:47]
	v_mfma_f32_16x16x32_bf16 v[36:39], v[144:147], v[188:191], v[36:39]
	v_mfma_f32_16x16x32_bf16 v[28:31], v[136:139], v[184:187], v[28:31]
	v_mfma_f32_16x16x32_bf16 v[20:23], v[144:147], v[184:187], v[20:23]
	v_mfma_f32_16x16x32_bf16 v[12:15], v[136:139], v[180:183], v[12:15]
	v_mfma_f32_16x16x32_bf16 v[4:7], v[144:147], v[180:183], v[4:7]
.LBB0_296:
	s_barrier
	s_setprio 0
	v_add_u32_e32 v0, 0x18000, v223
	ds_read_b128 v[148:151], v0
	ds_read_b128 v[152:155], v0 offset:1024
	ds_read_b128 v[156:159], v0 offset:2048
	ds_read_b128 v[160:163], v0 offset:3072
	v_add_u32_e32 v0, 0x1c000, v223
	ds_read_b128 v[132:135], v0
	ds_read_b128 v[136:139], v0 offset:1024
	ds_read_b128 v[140:143], v0 offset:2048
	ds_read_b128 v[144:147], v0 offset:3072
	s_add_u32 s42, s42, 0x40000
	s_addc_u32 s43, s43, 0
	s_mov_b32 m0, s59
	v_lshl_add_u64 v[212:213], s[42:43], 0, v[196:197]
	ds_read_b128 v[176:179], v224 offset:32768
	ds_read_b128 v[192:195], v224 offset:33792
	ds_read_b128 v[172:175], v224 offset:34816
	ds_read_b128 v[188:191], v224 offset:35840
	ds_read_b128 v[168:171], v224 offset:36864
	ds_read_b128 v[184:187], v224 offset:37888
	ds_read_b128 v[164:167], v224 offset:38912
	ds_read_b128 v[180:183], v224 offset:39936
	global_load_lds_dwordx4 v[212:213], off
	v_lshl_add_u64 v[212:213], s[42:43], 0, v[200:201]
	s_mov_b32 m0, s60
	s_nop 0
	global_load_lds_dwordx4 v[212:213], off
	s_waitcnt vmcnt(8)
	s_waitcnt lgkmcnt(0)
	s_setprio 1
	s_barrier
	v_mfma_f32_16x16x32_bf16 v[128:131], v[148:151], v[176:179], v[128:131]
	v_mfma_f32_16x16x32_bf16 v[124:127], v[156:159], v[176:179], v[124:127]
	v_mfma_f32_16x16x32_bf16 v[112:115], v[148:151], v[172:175], v[112:115]
	v_mfma_f32_16x16x32_bf16 v[108:111], v[156:159], v[172:175], v[108:111]
	v_mfma_f32_16x16x32_bf16 v[96:99], v[148:151], v[168:171], v[96:99]
	v_mfma_f32_16x16x32_bf16 v[92:95], v[156:159], v[168:171], v[92:95]
	v_mfma_f32_16x16x32_bf16 v[80:83], v[148:151], v[164:167], v[80:83]
	v_mfma_f32_16x16x32_bf16 v[76:79], v[156:159], v[164:167], v[76:79]
	v_mfma_f32_16x16x32_bf16 v[128:131], v[152:155], v[192:195], v[128:131]
	v_mfma_f32_16x16x32_bf16 v[124:127], v[160:163], v[192:195], v[124:127]
	v_mfma_f32_16x16x32_bf16 v[112:115], v[152:155], v[188:191], v[112:115]
	v_mfma_f32_16x16x32_bf16 v[108:111], v[160:163], v[188:191], v[108:111]
	v_mfma_f32_16x16x32_bf16 v[96:99], v[152:155], v[184:187], v[96:99]
	v_mfma_f32_16x16x32_bf16 v[92:95], v[160:163], v[184:187], v[92:95]
	v_mfma_f32_16x16x32_bf16 v[80:83], v[152:155], v[180:183], v[80:83]
	v_mfma_f32_16x16x32_bf16 v[76:79], v[160:163], v[180:183], v[76:79]
	v_mfma_f32_16x16x32_bf16 v[120:123], v[132:135], v[176:179], v[120:123]
	v_mfma_f32_16x16x32_bf16 v[116:119], v[140:143], v[176:179], v[116:119]
	v_mfma_f32_16x16x32_bf16 v[104:107], v[132:135], v[172:175], v[104:107]
	v_mfma_f32_16x16x32_bf16 v[100:103], v[140:143], v[172:175], v[100:103]
	v_mfma_f32_16x16x32_bf16 v[88:91], v[132:135], v[168:171], v[88:91]
	v_mfma_f32_16x16x32_bf16 v[84:87], v[140:143], v[168:171], v[84:87]
	v_mfma_f32_16x16x32_bf16 v[72:75], v[132:135], v[164:167], v[72:75]
	v_mfma_f32_16x16x32_bf16 v[68:71], v[140:143], v[164:167], v[68:71]
	v_mfma_f32_16x16x32_bf16 v[120:123], v[136:139], v[192:195], v[120:123]
	v_mfma_f32_16x16x32_bf16 v[116:119], v[144:147], v[192:195], v[116:119]
	v_mfma_f32_16x16x32_bf16 v[104:107], v[136:139], v[188:191], v[104:107]
	v_mfma_f32_16x16x32_bf16 v[100:103], v[144:147], v[188:191], v[100:103]
	v_mfma_f32_16x16x32_bf16 v[88:91], v[136:139], v[184:187], v[88:91]
	v_mfma_f32_16x16x32_bf16 v[84:87], v[144:147], v[184:187], v[84:87]
	v_mfma_f32_16x16x32_bf16 v[72:75], v[136:139], v[180:183], v[72:75]
	v_mfma_f32_16x16x32_bf16 v[68:71], v[144:147], v[180:183], v[68:71]
	s_barrier
	s_setprio 0
	s_and_b64 vcc, exec, s[4:5]
	s_cbranch_vccnz .LBB0_298
	ds_read_b128 v[176:179], v224 offset:49152
	ds_read_b128 v[192:195], v224 offset:50176
	ds_read_b128 v[172:175], v224 offset:51200
	ds_read_b128 v[188:191], v224 offset:52224
	ds_read_b128 v[168:171], v224 offset:53248
	ds_read_b128 v[184:187], v224 offset:54272
	ds_read_b128 v[164:167], v224 offset:55296
	ds_read_b128 v[180:183], v224 offset:56320
; #define PG8_STAGE(bufoff, gbase, voff) do { _Pragma("unroll") for (int _i = 0; _i < 2; ++_i) \
;         __builtin_amdgcn_global_load_lds((const unsigned*)((const char*)(gbase) + (voff)[_i]), (PG8_LAS unsigned*)(lds + (bufoff) + ldsw + _i * 8192), 16, 0, 0); } while (0)
; #define PG8_LDA(dst, b, h) do { _Pragma("unroll") for (int m = 0; m < 4; ++m) _Pragma("unroll") for (int k = 0; k < 2; ++k) dst[m][k] = *(const PG8_LAS bf16x8*)(lds + PG8_SA(b, h) + aoff + m * 2048 + k * 1024); } while (0)
; #define PG8_MMA(ai, bj, At, Bt) do { __builtin_amdgcn_s_setprio(1); _Pragma("unroll") for (int m = 0; m < 4; ++m) _Pragma("unroll") for (int n = 0; n < 2; ++n) _Pragma("unroll") for (int k = 0; k < 2; ++k) \
;         acc[ai][bj][m][n] = __builtin_amdgcn_mfma_f32_16x16x32_bf16(Bt[n][k], At[m][k], acc[ai][bj][m][n], 0, 0, 0); __builtin_amdgcn_s_setprio(0); } while (0)
; #define PG8_WAIT_V(n) asm volatile("s_waitcnt vmcnt(" #n ")" ::: "memory")
; #define PG8_WAIT_L(n) asm volatile("s_waitcnt lgkmcnt(" #n ")" ::: "memory")
; #define PG8_BAR __builtin_amdgcn_s_barrier()
; #define PG8_SCHED __builtin_amdgcn_sched_barrier(0)
; template <class Epi, class Sched, bool ALIGN_EPI = false, bool SP2 = false>
; __device__ __forceinline__ void gemm_phase(PG8_LAS unsigned char* lds, const Gemm g, const Sched& S, const Epi& E) {
;     ...
;             if (full) PG8_LDA(At, 1, 1); PG8_STAGE(PG8_SB(1, 0), b3, voffB); PG8_STAGE(PG8_SB(1, 1), b3 + hstep, voffB); PG8_STAGE(PG8_SA(1, 0), a3, voffA);
;             PG8_WAIT_V(8); PG8_WAIT_L(0); PG8_BAR; if (full) { PG8_MMA(1, 0, At, B0); PG8_MMA(1, 1, At, B1); } PG8_BAR; PG8_SCHED;
.LBB0_298:
	s_mov_b32 m0, s61
	v_lshl_add_u64 v[2:3], v[2:3], 0, s[52:53]
	s_add_u32 s38, s38, 0x40080
	global_load_lds_dwordx4 v[2:3], off
	v_lshl_add_u64 v[2:3], v[208:209], 0, s[52:53]
	s_mov_b32 m0, s62
	s_addc_u32 s39, s39, 0
	global_load_lds_dwordx4 v[2:3], off
	v_lshl_add_u64 v[2:3], s[38:39], 0, v[198:199]
	s_mov_b32 m0, s65
	s_and_b64 vcc, exec, s[4:5]
	global_load_lds_dwordx4 v[2:3], off
	v_lshl_add_u64 v[2:3], s[38:39], 0, v[202:203]
	s_mov_b32 m0, s68
	s_nop 0
	global_load_lds_dwordx4 v[2:3], off
	v_lshl_add_u64 v[2:3], v[210:211], 0, s[52:53]
	s_mov_b32 m0, s63
	s_nop 0
	global_load_lds_dwordx4 v[2:3], off
	v_lshl_add_u64 v[2:3], v[220:221], 0, s[52:53]
	s_mov_b32 m0, s64
	s_nop 0
	global_load_lds_dwordx4 v[2:3], off
	s_waitcnt vmcnt(8)
	s_waitcnt lgkmcnt(0)
	s_setprio 1
	s_barrier
	s_cbranch_vccnz .LBB0_291
	s_setprio 1
	v_mfma_f32_16x16x32_bf16 v[64:67], v[148:151], v[176:179], v[64:67]
	v_mfma_f32_16x16x32_bf16 v[56:59], v[156:159], v[176:179], v[56:59]
	v_mfma_f32_16x16x32_bf16 v[48:51], v[148:151], v[172:175], v[48:51]
	v_mfma_f32_16x16x32_bf16 v[40:43], v[156:159], v[172:175], v[40:43]
	v_mfma_f32_16x16x32_bf16 v[32:35], v[148:151], v[168:171], v[32:35]
	v_mfma_f32_16x16x32_bf16 v[24:27], v[156:159], v[168:171], v[24:27]
	v_mfma_f32_16x16x32_bf16 v[16:19], v[148:151], v[164:167], v[16:19]
	v_mfma_f32_16x16x32_bf16 v[8:11], v[156:159], v[164:167], v[8:11]
	v_mfma_f32_16x16x32_bf16 v[64:67], v[152:155], v[192:195], v[64:67]
	v_mfma_f32_16x16x32_bf16 v[56:59], v[160:163], v[192:195], v[56:59]
	v_mfma_f32_16x16x32_bf16 v[48:51], v[152:155], v[188:191], v[48:51]
	v_mfma_f32_16x16x32_bf16 v[40:43], v[160:163], v[188:191], v[40:43]
	v_mfma_f32_16x16x32_bf16 v[32:35], v[152:155], v[184:187], v[32:35]
	v_mfma_f32_16x16x32_bf16 v[24:27], v[160:163], v[184:187], v[24:27]
	v_mfma_f32_16x16x32_bf16 v[16:19], v[152:155], v[180:183], v[16:19]
	v_mfma_f32_16x16x32_bf16 v[8:11], v[160:163], v[180:183], v[8:11]
	v_mfma_f32_16x16x32_bf16 v[60:63], v[132:135], v[176:179], v[60:63]
	v_mfma_f32_16x16x32_bf16 v[52:55], v[140:143], v[176:179], v[52:55]
	v_mfma_f32_16x16x32_bf16 v[44:47], v[132:135], v[172:175], v[44:47]
	v_mfma_f32_16x16x32_bf16 v[36:39], v[140:143], v[172:175], v[36:39]
	v_mfma_f32_16x16x32_bf16 v[28:31], v[132:135], v[168:171], v[28:31]
	v_mfma_f32_16x16x32_bf16 v[20:23], v[140:143], v[168:171], v[20:23]
	v_mfma_f32_16x16x32_bf16 v[12:15], v[132:135], v[164:167], v[12:15]
	v_mfma_f32_16x16x32_bf16 v[2:5], v[140:143], v[164:167], v[4:7]
	v_mfma_f32_16x16x32_bf16 v[60:63], v[136:139], v[192:195], v[60:63]
	v_mfma_f32_16x16x32_bf16 v[52:55], v[144:147], v[192:195], v[52:55]
	v_mfma_f32_16x16x32_bf16 v[44:47], v[136:139], v[188:191], v[44:47]
	v_mfma_f32_16x16x32_bf16 v[36:39], v[144:147], v[188:191], v[36:39]
	v_mfma_f32_16x16x32_bf16 v[28:31], v[136:139], v[184:187], v[28:31]
	v_mfma_f32_16x16x32_bf16 v[20:23], v[144:147], v[184:187], v[20:23]
	v_mfma_f32_16x16x32_bf16 v[12:15], v[136:139], v[180:183], v[12:15]
	v_mfma_f32_16x16x32_bf16 v[4:7], v[144:147], v[180:183], v[2:5]
	s_branch .LBB0_291

; #define PG8_STAGE(bufoff, gbase, voff) do { _Pragma("unroll") for (int _i = 0; _i < 2; ++_i) \
;         __builtin_amdgcn_global_load_lds((const unsigned*)((const char*)(gbase) + (voff)[_i]), (PG8_LAS unsigned*)(lds + (bufoff) + ldsw + _i * 8192), 16, 0, 0); } while (0)
; #define PG8_LDA(dst, b, h) do { _Pragma("unroll") for (int m = 0; m < 4; ++m) _Pragma("unroll") for (int k = 0; k < 2; ++k) dst[m][k] = *(const PG8_LAS bf16x8*)(lds + PG8_SA(b, h) + aoff + m * 2048 + k * 1024); } while (0)
; #define PG8_LDB(dst, b, h) do { _Pragma("unroll") for (int n = 0; n < 2; ++n) _Pragma("unroll") for (int k = 0; k < 2; ++k) dst[n][k] = *(const PG8_LAS bf16x8*)(lds + PG8_SB(b, h) + boff + n * 2048 + k * 1024); } while (0)
; #define PG8_MMA(ai, bj, At, Bt) do { __builtin_amdgcn_s_setprio(1); _Pragma("unroll") for (int m = 0; m < 4; ++m) _Pragma("unroll") for (int n = 0; n < 2; ++n) _Pragma("unroll") for (int k = 0; k < 2; ++k) \
;         acc[ai][bj][m][n] = __builtin_amdgcn_mfma_f32_16x16x32_bf16(Bt[n][k], At[m][k], acc[ai][bj][m][n], 0, 0, 0); __builtin_amdgcn_s_setprio(0); } while (0)
; #define PG8_WAIT_V(n) asm volatile("s_waitcnt vmcnt(" #n ")" ::: "memory")
; #define PG8_WAIT_L(n) asm volatile("s_waitcnt lgkmcnt(" #n ")" ::: "memory")
; #define PG8_BAR __builtin_amdgcn_s_barrier()
; #define PG8_SCHED __builtin_amdgcn_sched_barrier(0)
; template <class Epi, class Sched, bool ALIGN_EPI = false, bool SP2 = false>
; __device__ __forceinline__ void gemm_phase(PG8_LAS unsigned char* lds, const Gemm g, const Sched& S, const Epi& E) {
;     ...
;             const bool last = (t == nt - 2);
;             const char* a1 = cA + (size_t)(t + 1) * kstep;
;             const char* a2 = last ? nA : cA + (size_t)(t + 2) * kstep; const char* b2 = last ? nB : cB + (size_t)(t + 2) * kstep;
;             const char* a3 = a2 + kstep; const char* b3 = b2 + kstep;
;             if (last && has_next) S.a_ready(nxt);
;             if constexpr (SP2) {
;             PG8_LDB(B0, 0, 0); PG8_LDB(B1, 0, 1); PG8_SCHED; PG8_LDA(At, 0, 0); PG8_STAGE(PG8_SA(1, 1), a1 + hstep, voffA);
;             PG8_WAIT_V(8); PG8_WAIT_L(0); PG8_BAR; PG8_MMA(0, 0, At, B0); PG8_MMA(0, 1, At, B1); PG8_BAR; PG8_SCHED;
;             if (full) PG8_LDA(At, 0, 1); PG8_STAGE(PG8_SB(0, 0), b2, voffB); PG8_STAGE(PG8_SB(0, 1), b2 + hstep, voffB); PG8_STAGE(PG8_SA(0, 0), a2, voffA);
.LBB0_382:
	s_add_u32 s30, s24, s28
	s_addc_u32 s31, s25, s29
	s_add_u32 s30, s30, 0x100
	s_addc_u32 s31, s31, 0
	s_add_u32 s65, s62, s28
	s_addc_u32 s68, s63, s29
	s_add_i32 s69, 0, 0x10000
	s_cmpk_eq_i32 s28, 0x1500
	s_cselect_b32 s35, s27, s31
	s_cselect_b32 s34, s26, s30
	v_add_u32_e32 v146, s69, v140
	s_cselect_b32 s31, s9, s68
	s_cselect_b32 s30, s8, s65
	s_add_i32 s65, 0, 0x14000
	ds_read_b128 v[142:145], v146
	ds_read_b128 v[154:157], v146 offset:1024
	ds_read_b128 v[158:161], v146 offset:2048
	ds_read_b128 v[162:165], v146 offset:3072
	v_add_u32_e32 v146, s65, v140
	ds_read_b128 v[166:169], v146
	ds_read_b128 v[170:173], v146 offset:1024
	ds_read_b128 v[174:177], v146 offset:2048
	ds_read_b128 v[178:181], v146 offset:3072
	v_lshl_add_u64 v[146:147], v[136:137], 0, s[28:29]
	s_add_i32 m0, s44, 0xc000
	ds_read_b128 v[182:185], v141
	ds_read_b128 v[186:189], v141 offset:1024
	ds_read_b128 v[190:193], v141 offset:2048
	ds_read_b128 v[194:197], v141 offset:3072
	ds_read_b128 v[198:201], v141 offset:4096
	ds_read_b128 v[202:205], v141 offset:5120
	ds_read_b128 v[206:209], v141 offset:6144
	ds_read_b128 v[220:223], v141 offset:7168
	global_load_lds_dwordx4 v[146:147], off
	v_lshl_add_u64 v[146:147], v[138:139], 0, s[28:29]
	s_add_i32 m0, s44, 0xe000
	s_nop 0
	global_load_lds_dwordx4 v[146:147], off
	s_waitcnt vmcnt(8)
	s_waitcnt lgkmcnt(0)
	s_setprio 1
	s_barrier
	v_mfma_f32_16x16x32_bf16 v[114:117], v[142:145], v[182:185], v[114:117]
	v_mfma_f32_16x16x32_bf16 v[82:85], v[158:161], v[182:185], v[82:85]
	v_mfma_f32_16x16x32_bf16 v[122:125], v[142:145], v[190:193], v[122:125]
	v_mfma_f32_16x16x32_bf16 v[94:97], v[158:161], v[190:193], v[94:97]
	v_mfma_f32_16x16x32_bf16 v[126:129], v[142:145], v[198:201], v[126:129]
	v_mfma_f32_16x16x32_bf16 v[106:109], v[158:161], v[198:201], v[106:109]
	v_mfma_f32_16x16x32_bf16 v[118:121], v[142:145], v[206:209], v[118:121]
	v_mfma_f32_16x16x32_bf16 v[110:113], v[158:161], v[206:209], v[110:113]
	v_mfma_f32_16x16x32_bf16 v[114:117], v[154:157], v[186:189], v[114:117]
	v_mfma_f32_16x16x32_bf16 v[82:85], v[162:165], v[186:189], v[82:85]
	v_mfma_f32_16x16x32_bf16 v[122:125], v[154:157], v[194:197], v[122:125]
	v_mfma_f32_16x16x32_bf16 v[94:97], v[162:165], v[194:197], v[94:97]
	v_mfma_f32_16x16x32_bf16 v[126:129], v[154:157], v[202:205], v[126:129]
	v_mfma_f32_16x16x32_bf16 v[106:109], v[162:165], v[202:205], v[106:109]
	v_mfma_f32_16x16x32_bf16 v[118:121], v[154:157], v[220:223], v[118:121]
	v_mfma_f32_16x16x32_bf16 v[110:113], v[162:165], v[220:223], v[110:113]
	v_mfma_f32_16x16x32_bf16 v[26:29], v[166:169], v[182:185], v[26:29]
	v_mfma_f32_16x16x32_bf16 v[2:5], v[174:177], v[182:185], v[2:5]
	v_mfma_f32_16x16x32_bf16 v[34:37], v[166:169], v[190:193], v[34:37]
	v_mfma_f32_16x16x32_bf16 v[6:9], v[174:177], v[190:193], v[6:9]
	v_mfma_f32_16x16x32_bf16 v[42:45], v[166:169], v[198:201], v[42:45]
	v_mfma_f32_16x16x32_bf16 v[10:13], v[174:177], v[198:201], v[10:13]
	v_mfma_f32_16x16x32_bf16 v[46:49], v[166:169], v[206:209], v[46:49]
	v_mfma_f32_16x16x32_bf16 v[14:17], v[174:177], v[206:209], v[14:17]
	v_mfma_f32_16x16x32_bf16 v[26:29], v[170:173], v[186:189], v[26:29]
	v_mfma_f32_16x16x32_bf16 v[2:5], v[178:181], v[186:189], v[2:5]
	v_mfma_f32_16x16x32_bf16 v[34:37], v[170:173], v[194:197], v[34:37]
	v_mfma_f32_16x16x32_bf16 v[6:9], v[178:181], v[194:197], v[6:9]
	v_mfma_f32_16x16x32_bf16 v[42:45], v[170:173], v[202:205], v[42:45]
	v_mfma_f32_16x16x32_bf16 v[10:13], v[178:181], v[202:205], v[10:13]
	v_mfma_f32_16x16x32_bf16 v[46:49], v[170:173], v[220:223], v[46:49]
	v_mfma_f32_16x16x32_bf16 v[14:17], v[178:181], v[220:223], v[14:17]
	s_barrier
	s_setprio 0
	s_add_i32 s68, s69, s43
	v_lshl_add_u64 v[146:147], s[30:31], 0, v[0:1]
	s_mov_b32 m0, s68
	ds_read_b128 v[182:185], v141 offset:16384
	ds_read_b128 v[186:189], v141 offset:17408
	ds_read_b128 v[190:193], v141 offset:18432
	ds_read_b128 v[194:197], v141 offset:19456
	ds_read_b128 v[198:201], v141 offset:20480
	ds_read_b128 v[202:205], v141 offset:21504
	ds_read_b128 v[206:209], v141 offset:22528
	ds_read_b128 v[220:223], v141 offset:23552
	global_load_lds_dwordx4 v[146:147], off
	s_add_i32 m0, s68, 0x2000
	s_add_u32 s68, s30, 0xb0000
	v_lshl_add_u64 v[150:151], s[30:31], 0, v[130:131]
	s_addc_u32 s69, s31, 0
	s_add_i32 s65, s65, s43
	global_load_lds_dwordx4 v[150:151], off
	v_lshl_add_u64 v[210:211], s[68:69], 0, v[0:1]
	s_mov_b32 m0, s65
	v_lshl_add_u64 v[212:213], s[34:35], 0, v[130:131]
	global_load_lds_dwordx4 v[210:211], off
	v_lshl_add_u64 v[210:211], s[68:69], 0, v[130:131]
	s_add_i32 m0, s65, 0x2000
	s_nop 0
	global_load_lds_dwordx4 v[210:211], off
	v_lshl_add_u64 v[210:211], s[34:35], 0, v[0:1]
	s_mov_b32 m0, s44
	s_nop 0
	global_load_lds_dwordx4 v[210:211], off
	s_mov_b32 m0, s45
	s_nop 0
	global_load_lds_dwordx4 v[212:213], off
	s_waitcnt vmcnt(8)
	s_waitcnt lgkmcnt(0)
	s_setprio 1
	s_barrier
; #define PG8_STAGE(bufoff, gbase, voff) do { _Pragma("unroll") for (int _i = 0; _i < 2; ++_i) \
;         __builtin_amdgcn_global_load_lds((const unsigned*)((const char*)(gbase) + (voff)[_i]), (PG8_LAS unsigned*)(lds + (bufoff) + ldsw + _i * 8192), 16, 0, 0); } while (0)
; #define PG8_LDA(dst, b, h) do { _Pragma("unroll") for (int m = 0; m < 4; ++m) _Pragma("unroll") for (int k = 0; k < 2; ++k) dst[m][k] = *(const PG8_LAS bf16x8*)(lds + PG8_SA(b, h) + aoff + m * 2048 + k * 1024); } while (0)
; #define PG8_LDB(dst, b, h) do { _Pragma("unroll") for (int n = 0; n < 2; ++n) _Pragma("unroll") for (int k = 0; k < 2; ++k) dst[n][k] = *(const PG8_LAS bf16x8*)(lds + PG8_SB(b, h) + boff + n * 2048 + k * 1024); } while (0)
; #define PG8_MMA(ai, bj, At, Bt) do { __builtin_amdgcn_s_setprio(1); _Pragma("unroll") for (int m = 0; m < 4; ++m) _Pragma("unroll") for (int n = 0; n < 2; ++n) _Pragma("unroll") for (int k = 0; k < 2; ++k) \
;         acc[ai][bj][m][n] = __builtin_amdgcn_mfma_f32_16x16x32_bf16(Bt[n][k], At[m][k], acc[ai][bj][m][n], 0, 0, 0); __builtin_amdgcn_s_setprio(0); } while (0)
; #define PG8_WAIT_V(n) asm volatile("s_waitcnt vmcnt(" #n ")" ::: "memory")
; #define PG8_WAIT_L(n) asm volatile("s_waitcnt lgkmcnt(" #n ")" ::: "memory")
; #define PG8_BAR __builtin_amdgcn_s_barrier()
; #define PG8_SCHED __builtin_amdgcn_sched_barrier(0)
; template <class Epi, class Sched, bool ALIGN_EPI = false, bool SP2 = false>
; __device__ __forceinline__ void gemm_phase(PG8_LAS unsigned char* lds, const Gemm g, const Sched& S, const Epi& E) {
;     ...
;             PG8_WAIT_V(8); PG8_WAIT_L(0); PG8_BAR; if (full) { PG8_MMA(1, 0, At, B0); PG8_MMA(1, 1, At, B1); } PG8_BAR; PG8_SCHED;
;             PG8_LDB(B0, 1, 0); PG8_LDB(B1, 1, 1); PG8_SCHED; PG8_LDA(At, 1, 0); PG8_STAGE(PG8_SA(0, 1), a2 + hstep, voffA);
;             PG8_WAIT_V(8); PG8_WAIT_L(0); PG8_BAR; PG8_MMA(0, 0, At, B0); PG8_MMA(0, 1, At, B1); PG8_BAR; PG8_SCHED;
	v_mfma_f32_16x16x32_bf16 v[102:105], v[142:145], v[182:185], v[102:105]
	v_mfma_f32_16x16x32_bf16 v[98:101], v[158:161], v[182:185], v[98:101]
	v_mfma_f32_16x16x32_bf16 v[90:93], v[142:145], v[190:193], v[90:93]
	v_mfma_f32_16x16x32_bf16 v[86:89], v[158:161], v[190:193], v[86:89]
	v_mfma_f32_16x16x32_bf16 v[78:81], v[142:145], v[198:201], v[78:81]
	v_mfma_f32_16x16x32_bf16 v[74:77], v[158:161], v[198:201], v[74:77]
	v_mfma_f32_16x16x32_bf16 v[70:73], v[142:145], v[206:209], v[70:73]
	v_mfma_f32_16x16x32_bf16 v[66:69], v[158:161], v[206:209], v[66:69]
	v_mfma_f32_16x16x32_bf16 v[102:105], v[154:157], v[186:189], v[102:105]
	v_mfma_f32_16x16x32_bf16 v[98:101], v[162:165], v[186:189], v[98:101]
	v_mfma_f32_16x16x32_bf16 v[90:93], v[154:157], v[194:197], v[90:93]
	v_mfma_f32_16x16x32_bf16 v[86:89], v[162:165], v[194:197], v[86:89]
	v_mfma_f32_16x16x32_bf16 v[78:81], v[154:157], v[202:205], v[78:81]
	v_mfma_f32_16x16x32_bf16 v[74:77], v[162:165], v[202:205], v[74:77]
	v_mfma_f32_16x16x32_bf16 v[70:73], v[154:157], v[220:223], v[70:73]
	v_mfma_f32_16x16x32_bf16 v[66:69], v[162:165], v[220:223], v[66:69]
	v_mfma_f32_16x16x32_bf16 v[54:57], v[166:169], v[182:185], v[54:57]
	v_mfma_f32_16x16x32_bf16 v[18:21], v[174:177], v[182:185], v[18:21]
	v_mfma_f32_16x16x32_bf16 v[58:61], v[166:169], v[190:193], v[58:61]
	v_mfma_f32_16x16x32_bf16 v[30:33], v[174:177], v[190:193], v[30:33]
	v_mfma_f32_16x16x32_bf16 v[62:65], v[166:169], v[198:201], v[62:65]
	v_mfma_f32_16x16x32_bf16 v[38:41], v[174:177], v[198:201], v[38:41]
	v_mfma_f32_16x16x32_bf16 v[50:53], v[166:169], v[206:209], v[50:53]
	v_mfma_f32_16x16x32_bf16 v[22:25], v[174:177], v[206:209], v[22:25]
	v_mfma_f32_16x16x32_bf16 v[54:57], v[170:173], v[186:189], v[54:57]
	v_mfma_f32_16x16x32_bf16 v[18:21], v[178:181], v[186:189], v[18:21]
	v_mfma_f32_16x16x32_bf16 v[58:61], v[170:173], v[194:197], v[58:61]
	v_mfma_f32_16x16x32_bf16 v[30:33], v[178:181], v[194:197], v[30:33]
	v_mfma_f32_16x16x32_bf16 v[62:65], v[170:173], v[202:205], v[62:65]
	v_mfma_f32_16x16x32_bf16 v[38:41], v[178:181], v[202:205], v[38:41]
	v_mfma_f32_16x16x32_bf16 v[50:53], v[170:173], v[220:223], v[50:53]
	v_mfma_f32_16x16x32_bf16 v[22:25], v[178:181], v[220:223], v[22:25]
	s_barrier
	s_setprio 0
	s_add_i32 s65, 0, 0x18000
	v_add_u32_e32 v149, s65, v140
	s_add_i32 s68, 0, 0x1c000
	ds_read_b128 v[142:145], v149
	ds_read_b128 v[154:157], v149 offset:1024
	ds_read_b128 v[158:161], v149 offset:2048
	ds_read_b128 v[162:165], v149 offset:3072
	v_add_u32_e32 v149, s68, v140
	ds_read_b128 v[166:169], v149
	ds_read_b128 v[170:173], v149 offset:1024
	ds_read_b128 v[174:177], v149 offset:2048
	ds_read_b128 v[178:181], v149 offset:3072
	s_add_u32 s34, s34, 0xb0000
	s_addc_u32 s35, s35, 0
	s_mov_b32 m0, s48
	v_lshl_add_u64 v[214:215], s[34:35], 0, v[0:1]
	ds_read_b128 v[182:185], v141 offset:32768
	ds_read_b128 v[186:189], v141 offset:33792
	ds_read_b128 v[190:193], v141 offset:34816
	ds_read_b128 v[194:197], v141 offset:35840
	ds_read_b128 v[198:201], v141 offset:36864
	ds_read_b128 v[202:205], v141 offset:37888
	ds_read_b128 v[206:209], v141 offset:38912
	ds_read_b128 v[220:223], v141 offset:39936
	global_load_lds_dwordx4 v[214:215], off
	v_lshl_add_u64 v[214:215], s[34:35], 0, v[130:131]
	s_mov_b32 m0, s54
	s_nop 0
	global_load_lds_dwordx4 v[214:215], off
	s_waitcnt vmcnt(8)
	s_waitcnt lgkmcnt(0)
	s_setprio 1
	s_barrier
	v_mfma_f32_16x16x32_bf16 v[114:117], v[142:145], v[182:185], v[114:117]
	v_mfma_f32_16x16x32_bf16 v[82:85], v[158:161], v[182:185], v[82:85]
	v_mfma_f32_16x16x32_bf16 v[122:125], v[142:145], v[190:193], v[122:125]
	v_mfma_f32_16x16x32_bf16 v[94:97], v[158:161], v[190:193], v[94:97]
	v_mfma_f32_16x16x32_bf16 v[126:129], v[142:145], v[198:201], v[126:129]
	v_mfma_f32_16x16x32_bf16 v[106:109], v[158:161], v[198:201], v[106:109]
	v_mfma_f32_16x16x32_bf16 v[118:121], v[142:145], v[206:209], v[118:121]
	v_mfma_f32_16x16x32_bf16 v[110:113], v[158:161], v[206:209], v[110:113]
	v_mfma_f32_16x16x32_bf16 v[114:117], v[154:157], v[186:189], v[114:117]
	v_mfma_f32_16x16x32_bf16 v[82:85], v[162:165], v[186:189], v[82:85]
	v_mfma_f32_16x16x32_bf16 v[122:125], v[154:157], v[194:197], v[122:125]
	v_mfma_f32_16x16x32_bf16 v[94:97], v[162:165], v[194:197], v[94:97]
	v_mfma_f32_16x16x32_bf16 v[126:129], v[154:157], v[202:205], v[126:129]
	v_mfma_f32_16x16x32_bf16 v[106:109], v[162:165], v[202:205], v[106:109]
	v_mfma_f32_16x16x32_bf16 v[118:121], v[154:157], v[220:223], v[118:121]
	v_mfma_f32_16x16x32_bf16 v[110:113], v[162:165], v[220:223], v[110:113]
	v_mfma_f32_16x16x32_bf16 v[26:29], v[166:169], v[182:185], v[26:29]
	v_mfma_f32_16x16x32_bf16 v[2:5], v[174:177], v[182:185], v[2:5]
	v_mfma_f32_16x16x32_bf16 v[34:37], v[166:169], v[190:193], v[34:37]
	v_mfma_f32_16x16x32_bf16 v[6:9], v[174:177], v[190:193], v[6:9]
	v_mfma_f32_16x16x32_bf16 v[42:45], v[166:169], v[198:201], v[42:45]
	v_mfma_f32_16x16x32_bf16 v[10:13], v[174:177], v[198:201], v[10:13]
	v_mfma_f32_16x16x32_bf16 v[46:49], v[166:169], v[206:209], v[46:49]
	v_mfma_f32_16x16x32_bf16 v[14:17], v[174:177], v[206:209], v[14:17]
	v_mfma_f32_16x16x32_bf16 v[26:29], v[170:173], v[186:189], v[26:29]
	v_mfma_f32_16x16x32_bf16 v[2:5], v[178:181], v[186:189], v[2:5]
	v_mfma_f32_16x16x32_bf16 v[34:37], v[170:173], v[194:197], v[34:37]
	v_mfma_f32_16x16x32_bf16 v[6:9], v[178:181], v[194:197], v[6:9]
	v_mfma_f32_16x16x32_bf16 v[42:45], v[170:173], v[202:205], v[42:45]
	v_mfma_f32_16x16x32_bf16 v[10:13], v[178:181], v[202:205], v[10:13]
	v_mfma_f32_16x16x32_bf16 v[46:49], v[170:173], v[220:223], v[46:49]
	v_mfma_f32_16x16x32_bf16 v[14:17], v[178:181], v[220:223], v[14:17]
	s_barrier
; #define PG8_STAGE(bufoff, gbase, voff) do { _Pragma("unroll") for (int _i = 0; _i < 2; ++_i) \
;         __builtin_amdgcn_global_load_lds((const unsigned*)((const char*)(gbase) + (voff)[_i]), (PG8_LAS unsigned*)(lds + (bufoff) + ldsw + _i * 8192), 16, 0, 0); } while (0)
; #define PG8_LDA(dst, b, h) do { _Pragma("unroll") for (int m = 0; m < 4; ++m) _Pragma("unroll") for (int k = 0; k < 2; ++k) dst[m][k] = *(const PG8_LAS bf16x8*)(lds + PG8_SA(b, h) + aoff + m * 2048 + k * 1024); } while (0)
; #define PG8_MMA(ai, bj, At, Bt) do { __builtin_amdgcn_s_setprio(1); _Pragma("unroll") for (int m = 0; m < 4; ++m) _Pragma("unroll") for (int n = 0; n < 2; ++n) _Pragma("unroll") for (int k = 0; k < 2; ++k) \
;         acc[ai][bj][m][n] = __builtin_amdgcn_mfma_f32_16x16x32_bf16(Bt[n][k], At[m][k], acc[ai][bj][m][n], 0, 0, 0); __builtin_amdgcn_s_setprio(0); } while (0)
; #define PG8_WAIT_V(n) asm volatile("s_waitcnt vmcnt(" #n ")" ::: "memory")
; #define PG8_WAIT_L(n) asm volatile("s_waitcnt lgkmcnt(" #n ")" ::: "memory")
; #define PG8_BAR __builtin_amdgcn_s_barrier()
; #define PG8_SCHED __builtin_amdgcn_sched_barrier(0)
; template <class Epi, class Sched, bool ALIGN_EPI = false, bool SP2 = false>
; __device__ __forceinline__ void gemm_phase(PG8_LAS unsigned char* lds, const Gemm g, const Sched& S, const Epi& E) {
;     ...
;             if (full) PG8_LDA(At, 1, 1); PG8_STAGE(PG8_SB(1, 0), b3, voffB); PG8_STAGE(PG8_SB(1, 1), b3 + hstep, voffB); PG8_STAGE(PG8_SA(1, 0), a3, voffA);
;             PG8_WAIT_V(8); PG8_WAIT_L(0); PG8_BAR; if (full) { PG8_MMA(1, 0, At, B0); PG8_MMA(1, 1, At, B1); } PG8_BAR; PG8_SCHED;
;     ...
;         if (!Sched::KEEP || (nxt.pn >> 2) == 0) {
; #pragma unroll
;         for (int a = 0; a < 2; ++a)
; #pragma unroll
;             for (int b = 0; b < 2; ++b)
; #pragma unroll
;                 for (int m = 0; m < 4; ++m)
; #pragma unroll
;                     for (int n = 0; n < 2; ++n) acc[a][b][m][n] = (f32x4){0.f, 0.f, 0.f, 0.f};
;         }
	s_setprio 0
	s_add_i32 s34, s65, s43
	v_lshl_add_u64 v[146:147], v[146:147], 0, s[52:53]
	s_mov_b32 m0, s34
	ds_read_b128 v[182:185], v141 offset:49152
	ds_read_b128 v[186:189], v141 offset:50176
	ds_read_b128 v[190:193], v141 offset:51200
	ds_read_b128 v[194:197], v141 offset:52224
	ds_read_b128 v[198:201], v141 offset:53248
	ds_read_b128 v[202:205], v141 offset:54272
	ds_read_b128 v[206:209], v141 offset:55296
	ds_read_b128 v[220:223], v141 offset:56320
	global_load_lds_dwordx4 v[146:147], off
	s_add_i32 m0, s34, 0x2000
	s_add_u32 s30, s30, 0xb0080
	v_lshl_add_u64 v[146:147], v[150:151], 0, s[52:53]
	s_addc_u32 s31, s31, 0
	s_add_i32 s34, s68, s43
	global_load_lds_dwordx4 v[146:147], off
	v_lshl_add_u64 v[146:147], s[30:31], 0, v[0:1]
	s_mov_b32 m0, s34
	s_nop 0
	global_load_lds_dwordx4 v[146:147], off
	v_lshl_add_u64 v[146:147], s[30:31], 0, v[130:131]
	s_add_i32 m0, s34, 0x2000
	s_nop 0
	global_load_lds_dwordx4 v[146:147], off
	v_lshl_add_u64 v[146:147], v[210:211], 0, s[52:53]
	s_mov_b32 m0, s55
	s_nop 0
	global_load_lds_dwordx4 v[146:147], off
	v_lshl_add_u64 v[146:147], v[212:213], 0, s[52:53]
	s_mov_b32 m0, s56
	s_nop 0
	global_load_lds_dwordx4 v[146:147], off
	s_waitcnt vmcnt(8)
	s_waitcnt lgkmcnt(0)
	s_setprio 1
	s_barrier
	v_mfma_f32_16x16x32_bf16 v[102:105], v[142:145], v[182:185], v[102:105]
	v_mfma_f32_16x16x32_bf16 v[98:101], v[158:161], v[182:185], v[98:101]
	v_mfma_f32_16x16x32_bf16 v[90:93], v[142:145], v[190:193], v[90:93]
	v_mfma_f32_16x16x32_bf16 v[86:89], v[158:161], v[190:193], v[86:89]
	v_mfma_f32_16x16x32_bf16 v[78:81], v[142:145], v[198:201], v[78:81]
	v_mfma_f32_16x16x32_bf16 v[74:77], v[158:161], v[198:201], v[74:77]
	v_mfma_f32_16x16x32_bf16 v[70:73], v[142:145], v[206:209], v[70:73]
	v_mfma_f32_16x16x32_bf16 v[66:69], v[158:161], v[206:209], v[66:69]
	v_mfma_f32_16x16x32_bf16 v[102:105], v[154:157], v[186:189], v[102:105]
	v_mfma_f32_16x16x32_bf16 v[98:101], v[162:165], v[186:189], v[98:101]
	v_mfma_f32_16x16x32_bf16 v[90:93], v[154:157], v[194:197], v[90:93]
	v_mfma_f32_16x16x32_bf16 v[86:89], v[162:165], v[194:197], v[86:89]
	v_mfma_f32_16x16x32_bf16 v[78:81], v[154:157], v[202:205], v[78:81]
	v_mfma_f32_16x16x32_bf16 v[74:77], v[162:165], v[202:205], v[74:77]
	v_mfma_f32_16x16x32_bf16 v[70:73], v[154:157], v[220:223], v[70:73]
	v_mfma_f32_16x16x32_bf16 v[66:69], v[162:165], v[220:223], v[66:69]
	v_mfma_f32_16x16x32_bf16 v[54:57], v[166:169], v[182:185], v[54:57]
	v_mfma_f32_16x16x32_bf16 v[18:21], v[174:177], v[182:185], v[18:21]
	v_mfma_f32_16x16x32_bf16 v[58:61], v[166:169], v[190:193], v[58:61]
	v_mfma_f32_16x16x32_bf16 v[30:33], v[174:177], v[190:193], v[30:33]
	v_mfma_f32_16x16x32_bf16 v[62:65], v[166:169], v[198:201], v[62:65]
	v_mfma_f32_16x16x32_bf16 v[38:41], v[174:177], v[198:201], v[38:41]
	v_mfma_f32_16x16x32_bf16 v[50:53], v[166:169], v[206:209], v[50:53]
	v_mfma_f32_16x16x32_bf16 v[22:25], v[174:177], v[206:209], v[22:25]
	v_mfma_f32_16x16x32_bf16 v[54:57], v[170:173], v[186:189], v[54:57]
	v_mfma_f32_16x16x32_bf16 v[18:21], v[178:181], v[186:189], v[18:21]
	v_mfma_f32_16x16x32_bf16 v[58:61], v[170:173], v[194:197], v[58:61]
	v_mfma_f32_16x16x32_bf16 v[30:33], v[178:181], v[194:197], v[30:33]
	v_mfma_f32_16x16x32_bf16 v[62:65], v[170:173], v[202:205], v[62:65]
	v_mfma_f32_16x16x32_bf16 v[38:41], v[178:181], v[202:205], v[38:41]
	v_mfma_f32_16x16x32_bf16 v[50:53], v[170:173], v[220:223], v[50:53]
	v_mfma_f32_16x16x32_bf16 v[22:25], v[178:181], v[220:223], v[22:25]
	s_barrier
	s_setprio 0
	s_add_i32 s64, s64, 2
	s_add_u32 s28, s28, 0x100
	s_addc_u32 s29, s29, 0
	s_cmp_gt_u32 s64, 41
	s_cbranch_scc0 .LBB0_382
	s_add_u32 s28, s62, 0xffffff00
	s_addc_u32 s29, s63, -1
	s_and_b64 vcc, exec, s[6:7]
	s_cbranch_vccnz .LBB0_369
	v_mov_b32_e32 v22, 0
	s_mov_b32 s18, s59
	s_mov_b32 s37, s60
	s_mov_b64 s[24:25], s[26:27]
	s_mov_b32 s58, s61
	v_mov_b32_e32 v23, v22
	v_mov_b32_e32 v24, v22
	v_mov_b32_e32 v25, v22
	v_mov_b32_e32 v50, v22
	v_mov_b32_e32 v51, v22
	v_mov_b32_e32 v52, v22
	v_mov_b32_e32 v53, v22
	v_mov_b32_e32 v38, v22
	v_mov_b32_e32 v39, v22
	v_mov_b32_e32 v40, v22
	v_mov_b32_e32 v41, v22
	v_mov_b32_e32 v62, v22
	v_mov_b32_e32 v63, v22
	v_mov_b32_e32 v64, v22
	v_mov_b32_e32 v65, v22
	v_mov_b32_e32 v30, v22
	v_mov_b32_e32 v31, v22
	v_mov_b32_e32 v32, v22
	v_mov_b32_e32 v33, v22
	v_mov_b32_e32 v58, v22
	v_mov_b32_e32 v59, v22
	v_mov_b32_e32 v60, v22
	v_mov_b32_e32 v61, v22
	v_mov_b32_e32 v18, v22
	v_mov_b32_e32 v19, v22
	v_mov_b32_e32 v20, v22
	v_mov_b32_e32 v21, v22
	v_mov_b32_e32 v54, v22
	v_mov_b32_e32 v55, v22
	v_mov_b32_e32 v56, v22
	v_mov_b32_e32 v57, v22
	v_mov_b32_e32 v66, v22
	v_mov_b32_e32 v67, v22
	v_mov_b32_e32 v68, v22
	v_mov_b32_e32 v69, v22
	v_mov_b32_e32 v70, v22
	v_mov_b32_e32 v71, v22
	v_mov_b32_e32 v72, v22
	v_mov_b32_e32 v73, v22
	v_mov_b32_e32 v74, v22
	v_mov_b32_e32 v75, v22
	v_mov_b32_e32 v76, v22
	v_mov_b32_e32 v77, v22
	v_mov_b32_e32 v78, v22
	v_mov_b32_e32 v79, v22
	v_mov_b32_e32 v80, v22
	v_mov_b32_e32 v81, v22
	v_mov_b32_e32 v86, v22
	v_mov_b32_e32 v87, v22
	v_mov_b32_e32 v88, v22
	v_mov_b32_e32 v89, v22
	v_mov_b32_e32 v90, v22
	v_mov_b32_e32 v91, v22
	v_mov_b32_e32 v92, v22
	v_mov_b32_e32 v93, v22
	v_mov_b32_e32 v98, v22
	v_mov_b32_e32 v99, v22
	v_mov_b32_e32 v100, v22
	v_mov_b32_e32 v101, v22
	v_mov_b32_e32 v102, v22
	v_mov_b32_e32 v103, v22
	v_mov_b32_e32 v104, v22
	v_mov_b32_e32 v105, v22
	v_mov_b32_e32 v14, v22
	v_mov_b32_e32 v15, v22
	v_mov_b32_e32 v16, v22
	v_mov_b32_e32 v17, v22
	v_mov_b32_e32 v46, v22
	v_mov_b32_e32 v47, v22
	v_mov_b32_e32 v48, v22
	v_mov_b32_e32 v49, v22
	v_mov_b32_e32 v10, v22
	v_mov_b32_e32 v11, v22
	v_mov_b32_e32 v12, v22
	v_mov_b32_e32 v13, v22
	v_mov_b32_e32 v42, v22
	v_mov_b32_e32 v43, v22
	v_mov_b32_e32 v44, v22
	v_mov_b32_e32 v45, v22
	v_mov_b32_e32 v6, v22
	v_mov_b32_e32 v7, v22
	v_mov_b32_e32 v8, v22
	v_mov_b32_e32 v9, v22
	v_mov_b32_e32 v34, v22
	v_mov_b32_e32 v35, v22
	v_mov_b32_e32 v36, v22
	v_mov_b32_e32 v37, v22
	v_mov_b32_e32 v2, v22
	v_mov_b32_e32 v3, v22
	v_mov_b32_e32 v4, v22
	v_mov_b32_e32 v5, v22
	v_mov_b32_e32 v26, v22
	v_mov_b32_e32 v27, v22
	v_mov_b32_e32 v28, v22
	v_mov_b32_e32 v29, v22
	v_mov_b32_e32 v110, v22
	v_mov_b32_e32 v111, v22
	v_mov_b32_e32 v112, v22
	v_mov_b32_e32 v113, v22
	v_mov_b32_e32 v118, v22
	v_mov_b32_e32 v119, v22
	v_mov_b32_e32 v120, v22
	v_mov_b32_e32 v121, v22
	v_mov_b32_e32 v106, v22
	v_mov_b32_e32 v107, v22
	v_mov_b32_e32 v108, v22
	v_mov_b32_e32 v109, v22
	v_mov_b32_e32 v126, v22
	v_mov_b32_e32 v127, v22
	v_mov_b32_e32 v128, v22
	v_mov_b32_e32 v129, v22
	v_mov_b32_e32 v94, v22
	v_mov_b32_e32 v95, v22
	v_mov_b32_e32 v96, v22
	v_mov_b32_e32 v97, v22
	v_mov_b32_e32 v122, v22
	v_mov_b32_e32 v123, v22
	v_mov_b32_e32 v124, v22
	v_mov_b32_e32 v125, v22
	v_mov_b32_e32 v82, v22
	v_mov_b32_e32 v83, v22
	v_mov_b32_e32 v84, v22
	v_mov_b32_e32 v85, v22
	v_mov_b32_e32 v114, v22
	v_mov_b32_e32 v115, v22
	v_mov_b32_e32 v116, v22
	v_mov_b32_e32 v117, v22
	s_andn2_b64 vcc, exec, s[4:5]
	s_cbranch_vccnz .LBB0_370

; #define PG8_STAGE(bufoff, gbase, voff) do { _Pragma("unroll") for (int _i = 0; _i < 2; ++_i) \
;         __builtin_amdgcn_global_load_lds((const unsigned*)((const char*)(gbase) + (voff)[_i]), (PG8_LAS unsigned*)(lds + (bufoff) + ldsw + _i * 8192), 16, 0, 0); } while (0)
; #define PG8_LDA(dst, b, h) do { _Pragma("unroll") for (int m = 0; m < 4; ++m) _Pragma("unroll") for (int k = 0; k < 2; ++k) dst[m][k] = *(const PG8_LAS bf16x8*)(lds + PG8_SA(b, h) + aoff + m * 2048 + k * 1024); } while (0)
; #define PG8_LDB(dst, b, h) do { _Pragma("unroll") for (int n = 0; n < 2; ++n) _Pragma("unroll") for (int k = 0; k < 2; ++k) dst[n][k] = *(const PG8_LAS bf16x8*)(lds + PG8_SB(b, h) + boff + n * 2048 + k * 1024); } while (0)
; #define PG8_MMA(ai, bj, At, Bt) do { __builtin_amdgcn_s_setprio(1); _Pragma("unroll") for (int m = 0; m < 4; ++m) _Pragma("unroll") for (int n = 0; n < 2; ++n) _Pragma("unroll") for (int k = 0; k < 2; ++k) \
;         acc[ai][bj][m][n] = __builtin_amdgcn_mfma_f32_16x16x32_bf16(Bt[n][k], At[m][k], acc[ai][bj][m][n], 0, 0, 0); __builtin_amdgcn_s_setprio(0); } while (0)
; #define PG8_WAIT_V(n) asm volatile("s_waitcnt vmcnt(" #n ")" ::: "memory")
; #define PG8_WAIT_L(n) asm volatile("s_waitcnt lgkmcnt(" #n ")" ::: "memory")
; #define PG8_BAR __builtin_amdgcn_s_barrier()
; #define PG8_SCHED __builtin_amdgcn_sched_barrier(0)
; template <class Epi, class Sched, bool ALIGN_EPI = false, bool SP2 = false>
; __device__ __forceinline__ void gemm_phase(PG8_LAS unsigned char* lds, const Gemm g, const Sched& S, const Epi& E) {
;     ...
;             const bool last = (t == nt - 2);
;             const char* a1 = cA + (size_t)(t + 1) * kstep;
;             const char* a2 = last ? nA : cA + (size_t)(t + 2) * kstep; const char* b2 = last ? nB : cB + (size_t)(t + 2) * kstep;
;             const char* a3 = a2 + kstep; const char* b3 = b2 + kstep;
;             if (last && has_next) S.a_ready(nxt);
;             if constexpr (SP2) {
;             PG8_LDB(B0, 0, 0); PG8_LDB(B1, 0, 1); PG8_SCHED; PG8_LDA(At, 0, 0); PG8_STAGE(PG8_SA(1, 1), a1 + hstep, voffA);
;             PG8_WAIT_V(8); PG8_WAIT_L(0); PG8_BAR; PG8_MMA(0, 0, At, B0); PG8_MMA(0, 1, At, B1); PG8_BAR; PG8_SCHED;
;             if (full) PG8_LDA(At, 0, 1); PG8_STAGE(PG8_SB(0, 0), b2, voffB); PG8_STAGE(PG8_SB(0, 1), b2 + hstep, voffB); PG8_STAGE(PG8_SA(0, 0), a2, voffA);
.LBB0_521:
	v_add_u32_e32 v0, 0x10000, v225
	ds_read_b128 v[148:151], v0
	ds_read_b128 v[152:155], v0 offset:1024
	ds_read_b128 v[156:159], v0 offset:2048
	ds_read_b128 v[160:163], v0 offset:3072
	v_add_u32_e32 v0, 0x14000, v225
	ds_read_b128 v[132:135], v0
	ds_read_b128 v[136:139], v0 offset:1024
	ds_read_b128 v[140:143], v0 offset:2048
	ds_read_b128 v[144:147], v0 offset:3072
	v_lshl_add_u64 v[2:3], s[34:35], 0, v[204:205]
	s_add_i32 m0, s27, 0xc000
	ds_read_b128 v[176:179], v241
	ds_read_b128 v[192:195], v241 offset:1024
	ds_read_b128 v[172:175], v241 offset:2048
	ds_read_b128 v[188:191], v241 offset:3072
	ds_read_b128 v[168:171], v241 offset:4096
	ds_read_b128 v[184:187], v241 offset:5120
	ds_read_b128 v[164:167], v241 offset:6144
	ds_read_b128 v[180:183], v241 offset:7168
	global_load_lds_dwordx4 v[2:3], off
	v_lshl_add_u64 v[2:3], s[34:35], 0, v[206:207]
	s_add_i32 m0, s27, 0xe000
	s_nop 0
	global_load_lds_dwordx4 v[2:3], off
	s_waitcnt vmcnt(8)
	s_waitcnt lgkmcnt(0)
	s_setprio 1
	s_barrier
	v_mfma_f32_16x16x32_bf16 v[128:131], v[148:151], v[176:179], v[128:131]
	v_mfma_f32_16x16x32_bf16 v[124:127], v[156:159], v[176:179], v[124:127]
	v_mfma_f32_16x16x32_bf16 v[112:115], v[148:151], v[172:175], v[112:115]
	v_mfma_f32_16x16x32_bf16 v[108:111], v[156:159], v[172:175], v[108:111]
	v_mfma_f32_16x16x32_bf16 v[96:99], v[148:151], v[168:171], v[96:99]
	v_mfma_f32_16x16x32_bf16 v[92:95], v[156:159], v[168:171], v[92:95]
	v_mfma_f32_16x16x32_bf16 v[80:83], v[148:151], v[164:167], v[80:83]
	v_mfma_f32_16x16x32_bf16 v[76:79], v[156:159], v[164:167], v[76:79]
	v_mfma_f32_16x16x32_bf16 v[128:131], v[152:155], v[192:195], v[128:131]
	v_mfma_f32_16x16x32_bf16 v[124:127], v[160:163], v[192:195], v[124:127]
	v_mfma_f32_16x16x32_bf16 v[112:115], v[152:155], v[188:191], v[112:115]
	v_mfma_f32_16x16x32_bf16 v[108:111], v[160:163], v[188:191], v[108:111]
	v_mfma_f32_16x16x32_bf16 v[96:99], v[152:155], v[184:187], v[96:99]
	v_mfma_f32_16x16x32_bf16 v[92:95], v[160:163], v[184:187], v[92:95]
	v_mfma_f32_16x16x32_bf16 v[80:83], v[152:155], v[180:183], v[80:83]
	v_mfma_f32_16x16x32_bf16 v[76:79], v[160:163], v[180:183], v[76:79]
	v_mfma_f32_16x16x32_bf16 v[120:123], v[132:135], v[176:179], v[120:123]
	v_mfma_f32_16x16x32_bf16 v[116:119], v[140:143], v[176:179], v[116:119]
	v_mfma_f32_16x16x32_bf16 v[104:107], v[132:135], v[172:175], v[104:107]
	v_mfma_f32_16x16x32_bf16 v[100:103], v[140:143], v[172:175], v[100:103]
	v_mfma_f32_16x16x32_bf16 v[88:91], v[132:135], v[168:171], v[88:91]
	v_mfma_f32_16x16x32_bf16 v[84:87], v[140:143], v[168:171], v[84:87]
	v_mfma_f32_16x16x32_bf16 v[72:75], v[132:135], v[164:167], v[72:75]
	v_mfma_f32_16x16x32_bf16 v[68:71], v[140:143], v[164:167], v[68:71]
	v_mfma_f32_16x16x32_bf16 v[120:123], v[136:139], v[192:195], v[120:123]
	v_mfma_f32_16x16x32_bf16 v[116:119], v[144:147], v[192:195], v[116:119]
	v_mfma_f32_16x16x32_bf16 v[104:107], v[136:139], v[188:191], v[104:107]
	v_mfma_f32_16x16x32_bf16 v[100:103], v[144:147], v[188:191], v[100:103]
	v_mfma_f32_16x16x32_bf16 v[88:91], v[136:139], v[184:187], v[88:91]
	v_mfma_f32_16x16x32_bf16 v[84:87], v[144:147], v[184:187], v[84:87]
	v_mfma_f32_16x16x32_bf16 v[72:75], v[136:139], v[180:183], v[72:75]
	v_mfma_f32_16x16x32_bf16 v[68:71], v[144:147], v[180:183], v[68:71]
	s_barrier
	s_setprio 0
	v_cndmask_b32_e64 v0, 0, 1, s[30:31]
	v_cmp_ne_u32_e64 s[4:5], 1, v0
	s_andn2_b64 vcc, exec, s[30:31]
	s_cbranch_vccnz .LBB0_523
	ds_read_b128 v[176:179], v241 offset:16384
	ds_read_b128 v[192:195], v241 offset:17408
	ds_read_b128 v[172:175], v241 offset:18432
	ds_read_b128 v[188:191], v241 offset:19456
	ds_read_b128 v[168:171], v241 offset:20480
	ds_read_b128 v[184:187], v241 offset:21504
	ds_read_b128 v[164:167], v241 offset:22528
	ds_read_b128 v[180:183], v241 offset:23552
.LBB0_523:
	s_add_u32 s36, s34, 0xfffc0080
	s_addc_u32 s37, s35, -1
	s_cmp_eq_u32 s82, 12
	s_cselect_b32 s39, s1, s37
	s_cselect_b32 s38, s19, s36
	s_cselect_b32 s37, s17, s81
	s_cselect_b32 s36, s29, s80
	s_mov_b32 m0, s49
	v_lshl_add_u64 v[2:3], s[36:37], 0, v[198:199]
	s_add_u32 s88, s36, 0x40000
	global_load_lds_dwordx4 v[2:3], off
	v_lshl_add_u64 v[208:209], s[36:37], 0, v[202:203]
	s_mov_b32 m0, s54
	s_addc_u32 s89, s37, 0
	global_load_lds_dwordx4 v[208:209], off
	v_lshl_add_u64 v[210:211], s[88:89], 0, v[198:199]
	s_mov_b32 m0, s55
	v_lshl_add_u64 v[220:221], s[38:39], 0, v[200:201]
	global_load_lds_dwordx4 v[210:211], off
	v_lshl_add_u64 v[210:211], s[88:89], 0, v[202:203]
	s_mov_b32 m0, s56
	s_and_b64 vcc, exec, s[4:5]
	global_load_lds_dwordx4 v[210:211], off
	v_lshl_add_u64 v[210:211], s[38:39], 0, v[196:197]
	s_mov_b32 m0, s27
	s_nop 0
	global_load_lds_dwordx4 v[210:211], off
	s_mov_b32 m0, s57
	s_nop 0
	global_load_lds_dwordx4 v[220:221], off
	s_waitcnt vmcnt(8)
	s_waitcnt lgkmcnt(0)
	s_setprio 1
	s_barrier
	s_cbranch_vccnz .LBB0_525
; #define PG8_STAGE(bufoff, gbase, voff) do { _Pragma("unroll") for (int _i = 0; _i < 2; ++_i) \
;         __builtin_amdgcn_global_load_lds((const unsigned*)((const char*)(gbase) + (voff)[_i]), (PG8_LAS unsigned*)(lds + (bufoff) + ldsw + _i * 8192), 16, 0, 0); } while (0)
; #define PG8_LDA(dst, b, h) do { _Pragma("unroll") for (int m = 0; m < 4; ++m) _Pragma("unroll") for (int k = 0; k < 2; ++k) dst[m][k] = *(const PG8_LAS bf16x8*)(lds + PG8_SA(b, h) + aoff + m * 2048 + k * 1024); } while (0)
; #define PG8_LDB(dst, b, h) do { _Pragma("unroll") for (int n = 0; n < 2; ++n) _Pragma("unroll") for (int k = 0; k < 2; ++k) dst[n][k] = *(const PG8_LAS bf16x8*)(lds + PG8_SB(b, h) + boff + n * 2048 + k * 1024); } while (0)
; #define PG8_MMA(ai, bj, At, Bt) do { __builtin_amdgcn_s_setprio(1); _Pragma("unroll") for (int m = 0; m < 4; ++m) _Pragma("unroll") for (int n = 0; n < 2; ++n) _Pragma("unroll") for (int k = 0; k < 2; ++k) \
;         acc[ai][bj][m][n] = __builtin_amdgcn_mfma_f32_16x16x32_bf16(Bt[n][k], At[m][k], acc[ai][bj][m][n], 0, 0, 0); __builtin_amdgcn_s_setprio(0); } while (0)
; #define PG8_WAIT_V(n) asm volatile("s_waitcnt vmcnt(" #n ")" ::: "memory")
; #define PG8_WAIT_L(n) asm volatile("s_waitcnt lgkmcnt(" #n ")" ::: "memory")
; #define PG8_BAR __builtin_amdgcn_s_barrier()
; #define PG8_SCHED __builtin_amdgcn_sched_barrier(0)
; template <class Epi, class Sched, bool ALIGN_EPI = false, bool SP2 = false>
; __device__ __forceinline__ void gemm_phase(PG8_LAS unsigned char* lds, const Gemm g, const Sched& S, const Epi& E) {
;     ...
;             PG8_WAIT_V(8); PG8_WAIT_L(0); PG8_BAR; if (full) { PG8_MMA(1, 0, At, B0); PG8_MMA(1, 1, At, B1); } PG8_BAR; PG8_SCHED;
;             PG8_LDB(B0, 1, 0); PG8_LDB(B1, 1, 1); PG8_SCHED; PG8_LDA(At, 1, 0); PG8_STAGE(PG8_SA(0, 1), a2 + hstep, voffA);
;             PG8_WAIT_V(8); PG8_WAIT_L(0); PG8_BAR; PG8_MMA(0, 0, At, B0); PG8_MMA(0, 1, At, B1); PG8_BAR; PG8_SCHED;
;             if (full) PG8_LDA(At, 1, 1); PG8_STAGE(PG8_SB(1, 0), b3, voffB); PG8_STAGE(PG8_SB(1, 1), b3 + hstep, voffB); PG8_STAGE(PG8_SA(1, 0), a3, voffA);
	s_setprio 1
	v_mfma_f32_16x16x32_bf16 v[64:67], v[148:151], v[176:179], v[64:67]
	v_mfma_f32_16x16x32_bf16 v[60:63], v[156:159], v[176:179], v[60:63]
	v_mfma_f32_16x16x32_bf16 v[48:51], v[148:151], v[172:175], v[48:51]
	v_mfma_f32_16x16x32_bf16 v[44:47], v[156:159], v[172:175], v[44:47]
	v_mfma_f32_16x16x32_bf16 v[32:35], v[148:151], v[168:171], v[32:35]
	v_mfma_f32_16x16x32_bf16 v[28:31], v[156:159], v[168:171], v[28:31]
	v_mfma_f32_16x16x32_bf16 v[16:19], v[148:151], v[164:167], v[16:19]
	v_mfma_f32_16x16x32_bf16 v[12:15], v[156:159], v[164:167], v[12:15]
	v_mfma_f32_16x16x32_bf16 v[64:67], v[152:155], v[192:195], v[64:67]
	v_mfma_f32_16x16x32_bf16 v[60:63], v[160:163], v[192:195], v[60:63]
	v_mfma_f32_16x16x32_bf16 v[48:51], v[152:155], v[188:191], v[48:51]
	v_mfma_f32_16x16x32_bf16 v[44:47], v[160:163], v[188:191], v[44:47]
	v_mfma_f32_16x16x32_bf16 v[32:35], v[152:155], v[184:187], v[32:35]
	v_mfma_f32_16x16x32_bf16 v[28:31], v[160:163], v[184:187], v[28:31]
	v_mfma_f32_16x16x32_bf16 v[16:19], v[152:155], v[180:183], v[16:19]
	v_mfma_f32_16x16x32_bf16 v[12:15], v[160:163], v[180:183], v[12:15]
	v_mfma_f32_16x16x32_bf16 v[56:59], v[132:135], v[176:179], v[56:59]
	v_mfma_f32_16x16x32_bf16 v[52:55], v[140:143], v[176:179], v[52:55]
	v_mfma_f32_16x16x32_bf16 v[40:43], v[132:135], v[172:175], v[40:43]
	v_mfma_f32_16x16x32_bf16 v[36:39], v[140:143], v[172:175], v[36:39]
	v_mfma_f32_16x16x32_bf16 v[24:27], v[132:135], v[168:171], v[24:27]
	v_mfma_f32_16x16x32_bf16 v[20:23], v[140:143], v[168:171], v[20:23]
	v_mfma_f32_16x16x32_bf16 v[8:11], v[132:135], v[164:167], v[8:11]
	v_mfma_f32_16x16x32_bf16 v[4:7], v[140:143], v[164:167], v[4:7]
	v_mfma_f32_16x16x32_bf16 v[56:59], v[136:139], v[192:195], v[56:59]
	v_mfma_f32_16x16x32_bf16 v[52:55], v[144:147], v[192:195], v[52:55]
	v_mfma_f32_16x16x32_bf16 v[40:43], v[136:139], v[188:191], v[40:43]
	v_mfma_f32_16x16x32_bf16 v[36:39], v[144:147], v[188:191], v[36:39]
	v_mfma_f32_16x16x32_bf16 v[24:27], v[136:139], v[184:187], v[24:27]
	v_mfma_f32_16x16x32_bf16 v[20:23], v[144:147], v[184:187], v[20:23]
	v_mfma_f32_16x16x32_bf16 v[8:11], v[136:139], v[180:183], v[8:11]
	v_mfma_f32_16x16x32_bf16 v[4:7], v[144:147], v[180:183], v[4:7]
.LBB0_525:
	s_barrier
	s_setprio 0
	v_add_u32_e32 v0, 0x18000, v225
	ds_read_b128 v[148:151], v0
	ds_read_b128 v[152:155], v0 offset:1024
	ds_read_b128 v[156:159], v0 offset:2048
	ds_read_b128 v[160:163], v0 offset:3072
	v_add_u32_e32 v0, 0x1c000, v225
	ds_read_b128 v[132:135], v0
	ds_read_b128 v[136:139], v0 offset:1024
	ds_read_b128 v[140:143], v0 offset:2048
	ds_read_b128 v[144:147], v0 offset:3072
	s_add_u32 s38, s38, 0x40000
	s_addc_u32 s39, s39, 0
	s_mov_b32 m0, s58
	v_lshl_add_u64 v[212:213], s[38:39], 0, v[196:197]
	ds_read_b128 v[176:179], v241 offset:32768
	ds_read_b128 v[192:195], v241 offset:33792
	ds_read_b128 v[172:175], v241 offset:34816
	ds_read_b128 v[188:191], v241 offset:35840
	ds_read_b128 v[168:171], v241 offset:36864
	ds_read_b128 v[184:187], v241 offset:37888
	ds_read_b128 v[164:167], v241 offset:38912
	ds_read_b128 v[180:183], v241 offset:39936
	global_load_lds_dwordx4 v[212:213], off
	v_lshl_add_u64 v[212:213], s[38:39], 0, v[200:201]
	s_mov_b32 m0, s59
	s_nop 0
	global_load_lds_dwordx4 v[212:213], off
	s_waitcnt vmcnt(8)
	s_waitcnt lgkmcnt(0)
	s_setprio 1
	s_barrier
	v_mfma_f32_16x16x32_bf16 v[128:131], v[148:151], v[176:179], v[128:131]
	v_mfma_f32_16x16x32_bf16 v[124:127], v[156:159], v[176:179], v[124:127]
	v_mfma_f32_16x16x32_bf16 v[112:115], v[148:151], v[172:175], v[112:115]
	v_mfma_f32_16x16x32_bf16 v[108:111], v[156:159], v[172:175], v[108:111]
	v_mfma_f32_16x16x32_bf16 v[96:99], v[148:151], v[168:171], v[96:99]
	v_mfma_f32_16x16x32_bf16 v[92:95], v[156:159], v[168:171], v[92:95]
	v_mfma_f32_16x16x32_bf16 v[80:83], v[148:151], v[164:167], v[80:83]
	v_mfma_f32_16x16x32_bf16 v[76:79], v[156:159], v[164:167], v[76:79]
	v_mfma_f32_16x16x32_bf16 v[128:131], v[152:155], v[192:195], v[128:131]
	v_mfma_f32_16x16x32_bf16 v[124:127], v[160:163], v[192:195], v[124:127]
	v_mfma_f32_16x16x32_bf16 v[112:115], v[152:155], v[188:191], v[112:115]
	v_mfma_f32_16x16x32_bf16 v[108:111], v[160:163], v[188:191], v[108:111]
	v_mfma_f32_16x16x32_bf16 v[96:99], v[152:155], v[184:187], v[96:99]
	v_mfma_f32_16x16x32_bf16 v[92:95], v[160:163], v[184:187], v[92:95]
	v_mfma_f32_16x16x32_bf16 v[80:83], v[152:155], v[180:183], v[80:83]
	v_mfma_f32_16x16x32_bf16 v[76:79], v[160:163], v[180:183], v[76:79]
	v_mfma_f32_16x16x32_bf16 v[120:123], v[132:135], v[176:179], v[120:123]
	v_mfma_f32_16x16x32_bf16 v[116:119], v[140:143], v[176:179], v[116:119]
	v_mfma_f32_16x16x32_bf16 v[104:107], v[132:135], v[172:175], v[104:107]
	v_mfma_f32_16x16x32_bf16 v[100:103], v[140:143], v[172:175], v[100:103]
	v_mfma_f32_16x16x32_bf16 v[88:91], v[132:135], v[168:171], v[88:91]
	v_mfma_f32_16x16x32_bf16 v[84:87], v[140:143], v[168:171], v[84:87]
	v_mfma_f32_16x16x32_bf16 v[72:75], v[132:135], v[164:167], v[72:75]
	v_mfma_f32_16x16x32_bf16 v[68:71], v[140:143], v[164:167], v[68:71]
	v_mfma_f32_16x16x32_bf16 v[120:123], v[136:139], v[192:195], v[120:123]
	v_mfma_f32_16x16x32_bf16 v[116:119], v[144:147], v[192:195], v[116:119]
	v_mfma_f32_16x16x32_bf16 v[104:107], v[136:139], v[188:191], v[104:107]
	v_mfma_f32_16x16x32_bf16 v[100:103], v[144:147], v[188:191], v[100:103]
	v_mfma_f32_16x16x32_bf16 v[88:91], v[136:139], v[184:187], v[88:91]
	v_mfma_f32_16x16x32_bf16 v[84:87], v[144:147], v[184:187], v[84:87]
	v_mfma_f32_16x16x32_bf16 v[72:75], v[136:139], v[180:183], v[72:75]
	v_mfma_f32_16x16x32_bf16 v[68:71], v[144:147], v[180:183], v[68:71]
	s_barrier
	s_setprio 0
	s_and_b64 vcc, exec, s[4:5]
	s_cbranch_vccnz .LBB0_527
	ds_read_b128 v[176:179], v241 offset:49152
	ds_read_b128 v[192:195], v241 offset:50176
	ds_read_b128 v[172:175], v241 offset:51200
	ds_read_b128 v[188:191], v241 offset:52224
	ds_read_b128 v[168:171], v241 offset:53248
	ds_read_b128 v[184:187], v241 offset:54272
	ds_read_b128 v[164:167], v241 offset:55296
	ds_read_b128 v[180:183], v241 offset:56320
; #define PG8_STAGE(bufoff, gbase, voff) do { _Pragma("unroll") for (int _i = 0; _i < 2; ++_i) \
;         __builtin_amdgcn_global_load_lds((const unsigned*)((const char*)(gbase) + (voff)[_i]), (PG8_LAS unsigned*)(lds + (bufoff) + ldsw + _i * 8192), 16, 0, 0); } while (0)
; #define PG8_LDA(dst, b, h) do { _Pragma("unroll") for (int m = 0; m < 4; ++m) _Pragma("unroll") for (int k = 0; k < 2; ++k) dst[m][k] = *(const PG8_LAS bf16x8*)(lds + PG8_SA(b, h) + aoff + m * 2048 + k * 1024); } while (0)
; #define PG8_MMA(ai, bj, At, Bt) do { __builtin_amdgcn_s_setprio(1); _Pragma("unroll") for (int m = 0; m < 4; ++m) _Pragma("unroll") for (int n = 0; n < 2; ++n) _Pragma("unroll") for (int k = 0; k < 2; ++k) \
;         acc[ai][bj][m][n] = __builtin_amdgcn_mfma_f32_16x16x32_bf16(Bt[n][k], At[m][k], acc[ai][bj][m][n], 0, 0, 0); __builtin_amdgcn_s_setprio(0); } while (0)
; #define PG8_WAIT_V(n) asm volatile("s_waitcnt vmcnt(" #n ")" ::: "memory")
; #define PG8_WAIT_L(n) asm volatile("s_waitcnt lgkmcnt(" #n ")" ::: "memory")
; #define PG8_BAR __builtin_amdgcn_s_barrier()
; #define PG8_SCHED __builtin_amdgcn_sched_barrier(0)
; template <class Epi, class Sched, bool ALIGN_EPI = false, bool SP2 = false>
; __device__ __forceinline__ void gemm_phase(PG8_LAS unsigned char* lds, const Gemm g, const Sched& S, const Epi& E) {
;     ...
;             if (full) PG8_LDA(At, 1, 1); PG8_STAGE(PG8_SB(1, 0), b3, voffB); PG8_STAGE(PG8_SB(1, 1), b3 + hstep, voffB); PG8_STAGE(PG8_SA(1, 0), a3, voffA);
;             PG8_WAIT_V(8); PG8_WAIT_L(0); PG8_BAR; if (full) { PG8_MMA(1, 0, At, B0); PG8_MMA(1, 1, At, B1); } PG8_BAR; PG8_SCHED;
.LBB0_527:
	s_mov_b32 m0, s62
	v_lshl_add_u64 v[2:3], v[2:3], 0, s[52:53]
	s_add_u32 s36, s36, 0x40080
	global_load_lds_dwordx4 v[2:3], off
	v_lshl_add_u64 v[2:3], v[208:209], 0, s[52:53]
	s_mov_b32 m0, s63
	s_addc_u32 s37, s37, 0
	global_load_lds_dwordx4 v[2:3], off
	v_lshl_add_u64 v[2:3], s[36:37], 0, v[198:199]
	s_mov_b32 m0, s68
	s_and_b64 vcc, exec, s[4:5]
	global_load_lds_dwordx4 v[2:3], off
	v_lshl_add_u64 v[2:3], s[36:37], 0, v[202:203]
	s_mov_b32 m0, s69
	s_nop 0
	global_load_lds_dwordx4 v[2:3], off
	v_lshl_add_u64 v[2:3], v[210:211], 0, s[52:53]
	s_mov_b32 m0, s64
	s_nop 0
	global_load_lds_dwordx4 v[2:3], off
	v_lshl_add_u64 v[2:3], v[220:221], 0, s[52:53]
	s_mov_b32 m0, s65
	s_nop 0
	global_load_lds_dwordx4 v[2:3], off
	s_waitcnt vmcnt(8)
	s_waitcnt lgkmcnt(0)
	s_setprio 1
	s_barrier
	s_cbranch_vccnz .LBB0_520
	s_setprio 1
	v_mfma_f32_16x16x32_bf16 v[64:67], v[148:151], v[176:179], v[64:67]
	v_mfma_f32_16x16x32_bf16 v[60:63], v[156:159], v[176:179], v[60:63]
	v_mfma_f32_16x16x32_bf16 v[48:51], v[148:151], v[172:175], v[48:51]
	v_mfma_f32_16x16x32_bf16 v[44:47], v[156:159], v[172:175], v[44:47]
	v_mfma_f32_16x16x32_bf16 v[32:35], v[148:151], v[168:171], v[32:35]
	v_mfma_f32_16x16x32_bf16 v[28:31], v[156:159], v[168:171], v[28:31]
	v_mfma_f32_16x16x32_bf16 v[16:19], v[148:151], v[164:167], v[16:19]
	v_mfma_f32_16x16x32_bf16 v[12:15], v[156:159], v[164:167], v[12:15]
	v_mfma_f32_16x16x32_bf16 v[64:67], v[152:155], v[192:195], v[64:67]
	v_mfma_f32_16x16x32_bf16 v[60:63], v[160:163], v[192:195], v[60:63]
	v_mfma_f32_16x16x32_bf16 v[48:51], v[152:155], v[188:191], v[48:51]
	v_mfma_f32_16x16x32_bf16 v[44:47], v[160:163], v[188:191], v[44:47]
	v_mfma_f32_16x16x32_bf16 v[32:35], v[152:155], v[184:187], v[32:35]
	v_mfma_f32_16x16x32_bf16 v[28:31], v[160:163], v[184:187], v[28:31]
	v_mfma_f32_16x16x32_bf16 v[16:19], v[152:155], v[180:183], v[16:19]
	v_mfma_f32_16x16x32_bf16 v[12:15], v[160:163], v[180:183], v[12:15]
	v_mfma_f32_16x16x32_bf16 v[56:59], v[132:135], v[176:179], v[56:59]
	v_mfma_f32_16x16x32_bf16 v[52:55], v[140:143], v[176:179], v[52:55]
	v_mfma_f32_16x16x32_bf16 v[40:43], v[132:135], v[172:175], v[40:43]
	v_mfma_f32_16x16x32_bf16 v[36:39], v[140:143], v[172:175], v[36:39]
	v_mfma_f32_16x16x32_bf16 v[24:27], v[132:135], v[168:171], v[24:27]
	v_mfma_f32_16x16x32_bf16 v[20:23], v[140:143], v[168:171], v[20:23]
	v_mfma_f32_16x16x32_bf16 v[8:11], v[132:135], v[164:167], v[8:11]
	v_mfma_f32_16x16x32_bf16 v[2:5], v[140:143], v[164:167], v[4:7]
	v_mfma_f32_16x16x32_bf16 v[56:59], v[136:139], v[192:195], v[56:59]
	v_mfma_f32_16x16x32_bf16 v[52:55], v[144:147], v[192:195], v[52:55]
	v_mfma_f32_16x16x32_bf16 v[40:43], v[136:139], v[188:191], v[40:43]
	v_mfma_f32_16x16x32_bf16 v[36:39], v[144:147], v[188:191], v[36:39]
	v_mfma_f32_16x16x32_bf16 v[24:27], v[136:139], v[184:187], v[24:27]
	v_mfma_f32_16x16x32_bf16 v[20:23], v[144:147], v[184:187], v[20:23]
	v_mfma_f32_16x16x32_bf16 v[8:11], v[136:139], v[180:183], v[8:11]
	v_mfma_f32_16x16x32_bf16 v[4:7], v[144:147], v[180:183], v[2:5]
	s_branch .LBB0_520

; #define PG8_STAGE(bufoff, gbase, voff) do { _Pragma("unroll") for (int _i = 0; _i < 2; ++_i) \
;         __builtin_amdgcn_global_load_lds((const unsigned*)((const char*)(gbase) + (voff)[_i]), (PG8_LAS unsigned*)(lds + (bufoff) + ldsw + _i * 8192), 16, 0, 0); } while (0)
; #define PG8_LDA(dst, b, h) do { _Pragma("unroll") for (int m = 0; m < 4; ++m) _Pragma("unroll") for (int k = 0; k < 2; ++k) dst[m][k] = *(const PG8_LAS bf16x8*)(lds + PG8_SA(b, h) + aoff + m * 2048 + k * 1024); } while (0)
; #define PG8_LDB(dst, b, h) do { _Pragma("unroll") for (int n = 0; n < 2; ++n) _Pragma("unroll") for (int k = 0; k < 2; ++k) dst[n][k] = *(const PG8_LAS bf16x8*)(lds + PG8_SB(b, h) + boff + n * 2048 + k * 1024); } while (0)
; #define PG8_MMA(ai, bj, At, Bt) do { __builtin_amdgcn_s_setprio(1); _Pragma("unroll") for (int m = 0; m < 4; ++m) _Pragma("unroll") for (int n = 0; n < 2; ++n) _Pragma("unroll") for (int k = 0; k < 2; ++k) \
;         acc[ai][bj][m][n] = __builtin_amdgcn_mfma_f32_16x16x32_bf16(Bt[n][k], At[m][k], acc[ai][bj][m][n], 0, 0, 0); __builtin_amdgcn_s_setprio(0); } while (0)
; #define PG8_WAIT_V(n) asm volatile("s_waitcnt vmcnt(" #n ")" ::: "memory")
; #define PG8_WAIT_L(n) asm volatile("s_waitcnt lgkmcnt(" #n ")" ::: "memory")
; #define PG8_BAR __builtin_amdgcn_s_barrier()
; #define PG8_SCHED __builtin_amdgcn_sched_barrier(0)
; template <class Epi, class Sched, bool ALIGN_EPI = false, bool SP2 = false>
; __device__ __forceinline__ void gemm_phase(PG8_LAS unsigned char* lds, const Gemm g, const Sched& S, const Epi& E) {
;     ...
;             const bool last = (t == nt - 2);
;             const char* a1 = cA + (size_t)(t + 1) * kstep;
;             const char* a2 = last ? nA : cA + (size_t)(t + 2) * kstep; const char* b2 = last ? nB : cB + (size_t)(t + 2) * kstep;
;             const char* a3 = a2 + kstep; const char* b3 = b2 + kstep;
;             if (last && has_next) S.a_ready(nxt);
;             if constexpr (SP2) {
;             PG8_LDB(B0, 0, 0); PG8_LDB(B1, 0, 1); PG8_SCHED; PG8_LDA(At, 0, 0); PG8_STAGE(PG8_SA(1, 1), a1 + hstep, voffA);
;             PG8_WAIT_V(8); PG8_WAIT_L(0); PG8_BAR; PG8_MMA(0, 0, At, B0); PG8_MMA(0, 1, At, B1); PG8_BAR; PG8_SCHED;
;             if (full) PG8_LDA(At, 0, 1); PG8_STAGE(PG8_SB(0, 0), b2, voffB); PG8_STAGE(PG8_SB(0, 1), b2 + hstep, voffB); PG8_STAGE(PG8_SA(0, 0), a2, voffA);
.LBB0_1038:
	s_add_u32 s27, s6, 0xfffe0080
	s_addc_u32 s28, s7, -1
	s_add_i32 s54, 0, 0x10000
	s_cmp_eq_u32 s25, 4
	s_cselect_b32 s31, s21, s28
	s_cselect_b32 s30, s20, s27
	v_add_u32_e32 v0, s54, v179
	s_cselect_b32 s29, s0, s19
	s_cselect_b32 s28, s1, s17
	s_add_i32 s27, 0, 0x14000
	ds_read_b128 v[144:147], v0
	ds_read_b128 v[148:151], v0 offset:1024
	ds_read_b128 v[152:155], v0 offset:2048
	ds_read_b128 v[156:159], v0 offset:3072
	v_add_u32_e32 v0, s27, v179
	ds_read_b128 v[160:163], v0
	ds_read_b128 v[164:167], v0 offset:1024
	ds_read_b128 v[168:171], v0 offset:2048
	ds_read_b128 v[172:175], v0 offset:3072
	v_lshl_add_u64 v[2:3], s[6:7], 0, v[140:141]
	s_add_i32 m0, s39, 0xc000
	ds_read_b128 v[182:185], v181
	ds_read_b128 v[186:189], v181 offset:1024
	ds_read_b128 v[190:193], v181 offset:2048
	ds_read_b128 v[194:197], v181 offset:3072
	ds_read_b128 v[198:201], v181 offset:4096
	ds_read_b128 v[202:205], v181 offset:5120
	ds_read_b128 v[206:209], v181 offset:6144
	ds_read_b128 v[220:223], v181 offset:7168
	global_load_lds_dwordx4 v[2:3], off
	v_lshl_add_u64 v[2:3], s[6:7], 0, v[142:143]
	s_add_i32 m0, s39, 0xe000
	s_nop 0
	global_load_lds_dwordx4 v[2:3], off
	s_waitcnt vmcnt(8)
	s_waitcnt lgkmcnt(0)
	s_setprio 1
	s_barrier
	v_mfma_f32_16x16x32_bf16 v[128:131], v[144:147], v[182:185], v[128:131]
	v_mfma_f32_16x16x32_bf16 v[124:127], v[152:155], v[182:185], v[124:127]
	v_mfma_f32_16x16x32_bf16 v[120:123], v[144:147], v[190:193], v[120:123]
	v_mfma_f32_16x16x32_bf16 v[116:119], v[152:155], v[190:193], v[116:119]
	v_mfma_f32_16x16x32_bf16 v[112:115], v[144:147], v[198:201], v[112:115]
	v_mfma_f32_16x16x32_bf16 v[108:111], v[152:155], v[198:201], v[108:111]
	v_mfma_f32_16x16x32_bf16 v[104:107], v[144:147], v[206:209], v[104:107]
	v_mfma_f32_16x16x32_bf16 v[100:103], v[152:155], v[206:209], v[100:103]
	v_mfma_f32_16x16x32_bf16 v[128:131], v[148:151], v[186:189], v[128:131]
	v_mfma_f32_16x16x32_bf16 v[124:127], v[156:159], v[186:189], v[124:127]
	v_mfma_f32_16x16x32_bf16 v[120:123], v[148:151], v[194:197], v[120:123]
	v_mfma_f32_16x16x32_bf16 v[116:119], v[156:159], v[194:197], v[116:119]
	v_mfma_f32_16x16x32_bf16 v[112:115], v[148:151], v[202:205], v[112:115]
	v_mfma_f32_16x16x32_bf16 v[108:111], v[156:159], v[202:205], v[108:111]
	v_mfma_f32_16x16x32_bf16 v[104:107], v[148:151], v[220:223], v[104:107]
	v_mfma_f32_16x16x32_bf16 v[100:103], v[156:159], v[220:223], v[100:103]
	v_mfma_f32_16x16x32_bf16 v[96:99], v[160:163], v[182:185], v[96:99]
	v_mfma_f32_16x16x32_bf16 v[92:95], v[168:171], v[182:185], v[92:95]
	v_mfma_f32_16x16x32_bf16 v[88:91], v[160:163], v[190:193], v[88:91]
	v_mfma_f32_16x16x32_bf16 v[84:87], v[168:171], v[190:193], v[84:87]
	v_mfma_f32_16x16x32_bf16 v[80:83], v[160:163], v[198:201], v[80:83]
	v_mfma_f32_16x16x32_bf16 v[76:79], v[168:171], v[198:201], v[76:79]
	v_mfma_f32_16x16x32_bf16 v[72:75], v[160:163], v[206:209], v[72:75]
	v_mfma_f32_16x16x32_bf16 v[68:71], v[168:171], v[206:209], v[68:71]
	v_mfma_f32_16x16x32_bf16 v[96:99], v[164:167], v[186:189], v[96:99]
	v_mfma_f32_16x16x32_bf16 v[92:95], v[172:175], v[186:189], v[92:95]
	v_mfma_f32_16x16x32_bf16 v[88:91], v[164:167], v[194:197], v[88:91]
	v_mfma_f32_16x16x32_bf16 v[84:87], v[172:175], v[194:197], v[84:87]
	v_mfma_f32_16x16x32_bf16 v[80:83], v[164:167], v[202:205], v[80:83]
	v_mfma_f32_16x16x32_bf16 v[76:79], v[172:175], v[202:205], v[76:79]
	v_mfma_f32_16x16x32_bf16 v[72:75], v[164:167], v[220:223], v[72:75]
	v_mfma_f32_16x16x32_bf16 v[68:71], v[172:175], v[220:223], v[68:71]
	s_barrier
	s_setprio 0
	s_add_i32 s54, s54, s38
	v_lshl_add_u64 v[176:177], s[28:29], 0, v[134:135]
	s_mov_b32 m0, s54
	ds_read_b128 v[182:185], v181 offset:16384
	ds_read_b128 v[186:189], v181 offset:17408
	ds_read_b128 v[190:193], v181 offset:18432
	ds_read_b128 v[194:197], v181 offset:19456
	ds_read_b128 v[198:201], v181 offset:20480
	ds_read_b128 v[202:205], v181 offset:21504
	ds_read_b128 v[206:209], v181 offset:22528
	ds_read_b128 v[220:223], v181 offset:23552
	global_load_lds_dwordx4 v[176:177], off
	s_add_i32 m0, s54, 0x2000
	s_add_u32 s54, s28, 0x20000
	v_lshl_add_u64 v[210:211], s[28:29], 0, v[138:139]
	s_addc_u32 s55, s29, 0
	s_add_i32 s27, s27, s38
	global_load_lds_dwordx4 v[210:211], off
	v_lshl_add_u64 v[2:3], s[54:55], 0, v[134:135]
	s_mov_b32 m0, s27
	v_lshl_add_u64 v[212:213], s[30:31], 0, v[132:133]
	global_load_lds_dwordx4 v[2:3], off
	v_lshl_add_u64 v[2:3], s[54:55], 0, v[138:139]
	s_add_i32 m0, s27, 0x2000
	v_lshl_add_u64 v[214:215], s[30:31], 0, v[136:137]
	global_load_lds_dwordx4 v[2:3], off
	s_mov_b32 m0, s39
	s_nop 0
	global_load_lds_dwordx4 v[212:213], off
	s_mov_b32 m0, s40
	s_nop 0
	global_load_lds_dwordx4 v[214:215], off
	s_waitcnt vmcnt(8)
	s_waitcnt lgkmcnt(0)
	s_setprio 1
	s_barrier
; #define PG8_STAGE(bufoff, gbase, voff) do { _Pragma("unroll") for (int _i = 0; _i < 2; ++_i) \
;         __builtin_amdgcn_global_load_lds((const unsigned*)((const char*)(gbase) + (voff)[_i]), (PG8_LAS unsigned*)(lds + (bufoff) + ldsw + _i * 8192), 16, 0, 0); } while (0)
; #define PG8_LDA(dst, b, h) do { _Pragma("unroll") for (int m = 0; m < 4; ++m) _Pragma("unroll") for (int k = 0; k < 2; ++k) dst[m][k] = *(const PG8_LAS bf16x8*)(lds + PG8_SA(b, h) + aoff + m * 2048 + k * 1024); } while (0)
; #define PG8_LDB(dst, b, h) do { _Pragma("unroll") for (int n = 0; n < 2; ++n) _Pragma("unroll") for (int k = 0; k < 2; ++k) dst[n][k] = *(const PG8_LAS bf16x8*)(lds + PG8_SB(b, h) + boff + n * 2048 + k * 1024); } while (0)
; #define PG8_MMA(ai, bj, At, Bt) do { __builtin_amdgcn_s_setprio(1); _Pragma("unroll") for (int m = 0; m < 4; ++m) _Pragma("unroll") for (int n = 0; n < 2; ++n) _Pragma("unroll") for (int k = 0; k < 2; ++k) \
;         acc[ai][bj][m][n] = __builtin_amdgcn_mfma_f32_16x16x32_bf16(Bt[n][k], At[m][k], acc[ai][bj][m][n], 0, 0, 0); __builtin_amdgcn_s_setprio(0); } while (0)
; #define PG8_WAIT_V(n) asm volatile("s_waitcnt vmcnt(" #n ")" ::: "memory")
; #define PG8_WAIT_L(n) asm volatile("s_waitcnt lgkmcnt(" #n ")" ::: "memory")
; #define PG8_BAR __builtin_amdgcn_s_barrier()
; #define PG8_SCHED __builtin_amdgcn_sched_barrier(0)
; template <class Epi, class Sched, bool ALIGN_EPI = false, bool SP2 = false>
; __device__ __forceinline__ void gemm_phase(PG8_LAS unsigned char* lds, const Gemm g, const Sched& S, const Epi& E) {
;     ...
;             PG8_WAIT_V(8); PG8_WAIT_L(0); PG8_BAR; if (full) { PG8_MMA(1, 0, At, B0); PG8_MMA(1, 1, At, B1); } PG8_BAR; PG8_SCHED;
;             PG8_LDB(B0, 1, 0); PG8_LDB(B1, 1, 1); PG8_SCHED; PG8_LDA(At, 1, 0); PG8_STAGE(PG8_SA(0, 1), a2 + hstep, voffA);
;             PG8_WAIT_V(8); PG8_WAIT_L(0); PG8_BAR; PG8_MMA(0, 0, At, B0); PG8_MMA(0, 1, At, B1); PG8_BAR; PG8_SCHED;
	v_mfma_f32_16x16x32_bf16 v[64:67], v[144:147], v[182:185], v[64:67]
	v_mfma_f32_16x16x32_bf16 v[60:63], v[152:155], v[182:185], v[60:63]
	v_mfma_f32_16x16x32_bf16 v[56:59], v[144:147], v[190:193], v[56:59]
	v_mfma_f32_16x16x32_bf16 v[52:55], v[152:155], v[190:193], v[52:55]
	v_mfma_f32_16x16x32_bf16 v[48:51], v[144:147], v[198:201], v[48:51]
	v_mfma_f32_16x16x32_bf16 v[44:47], v[152:155], v[198:201], v[44:47]
	v_mfma_f32_16x16x32_bf16 v[40:43], v[144:147], v[206:209], v[40:43]
	v_mfma_f32_16x16x32_bf16 v[36:39], v[152:155], v[206:209], v[36:39]
	v_mfma_f32_16x16x32_bf16 v[64:67], v[148:151], v[186:189], v[64:67]
	v_mfma_f32_16x16x32_bf16 v[60:63], v[156:159], v[186:189], v[60:63]
	v_mfma_f32_16x16x32_bf16 v[56:59], v[148:151], v[194:197], v[56:59]
	v_mfma_f32_16x16x32_bf16 v[52:55], v[156:159], v[194:197], v[52:55]
	v_mfma_f32_16x16x32_bf16 v[48:51], v[148:151], v[202:205], v[48:51]
	v_mfma_f32_16x16x32_bf16 v[44:47], v[156:159], v[202:205], v[44:47]
	v_mfma_f32_16x16x32_bf16 v[40:43], v[148:151], v[220:223], v[40:43]
	v_mfma_f32_16x16x32_bf16 v[36:39], v[156:159], v[220:223], v[36:39]
	v_mfma_f32_16x16x32_bf16 v[32:35], v[160:163], v[182:185], v[32:35]
	v_mfma_f32_16x16x32_bf16 v[28:31], v[168:171], v[182:185], v[28:31]
	v_mfma_f32_16x16x32_bf16 v[24:27], v[160:163], v[190:193], v[24:27]
	v_mfma_f32_16x16x32_bf16 v[20:23], v[168:171], v[190:193], v[20:23]
	v_mfma_f32_16x16x32_bf16 v[16:19], v[160:163], v[198:201], v[16:19]
	v_mfma_f32_16x16x32_bf16 v[12:15], v[168:171], v[198:201], v[12:15]
	v_mfma_f32_16x16x32_bf16 v[8:11], v[160:163], v[206:209], v[8:11]
	v_mfma_f32_16x16x32_bf16 v[2:5], v[168:171], v[206:209], v[4:7]
	v_mfma_f32_16x16x32_bf16 v[32:35], v[164:167], v[186:189], v[32:35]
	v_mfma_f32_16x16x32_bf16 v[28:31], v[172:175], v[186:189], v[28:31]
	v_mfma_f32_16x16x32_bf16 v[24:27], v[164:167], v[194:197], v[24:27]
	v_mfma_f32_16x16x32_bf16 v[20:23], v[172:175], v[194:197], v[20:23]
	v_mfma_f32_16x16x32_bf16 v[16:19], v[164:167], v[202:205], v[16:19]
	v_mfma_f32_16x16x32_bf16 v[12:15], v[172:175], v[202:205], v[12:15]
	v_mfma_f32_16x16x32_bf16 v[8:11], v[164:167], v[220:223], v[8:11]
	v_mfma_f32_16x16x32_bf16 v[2:5], v[172:175], v[220:223], v[2:5]
	s_barrier
	s_setprio 0
	s_add_i32 s27, 0, 0x18000
	v_add_u32_e32 v0, s27, v179
	s_add_i32 s54, 0, 0x1c000
	ds_read_b128 v[144:147], v0
	ds_read_b128 v[148:151], v0 offset:1024
	ds_read_b128 v[152:155], v0 offset:2048
	ds_read_b128 v[156:159], v0 offset:3072
	v_add_u32_e32 v0, s54, v179
	ds_read_b128 v[160:163], v0
	ds_read_b128 v[164:167], v0 offset:1024
	ds_read_b128 v[168:171], v0 offset:2048
	ds_read_b128 v[172:175], v0 offset:3072
	s_add_u32 s30, s30, 0x20000
	s_addc_u32 s31, s31, 0
	s_mov_b32 m0, s41
	v_lshl_add_u64 v[6:7], s[30:31], 0, v[132:133]
	ds_read_b128 v[182:185], v181 offset:32768
	ds_read_b128 v[186:189], v181 offset:33792
	ds_read_b128 v[190:193], v181 offset:34816
	ds_read_b128 v[194:197], v181 offset:35840
	ds_read_b128 v[198:201], v181 offset:36864
	ds_read_b128 v[202:205], v181 offset:37888
	ds_read_b128 v[206:209], v181 offset:38912
	ds_read_b128 v[220:223], v181 offset:39936
	global_load_lds_dwordx4 v[6:7], off
	v_lshl_add_u64 v[6:7], s[30:31], 0, v[136:137]
	s_mov_b32 m0, s42
	s_nop 0
	global_load_lds_dwordx4 v[6:7], off
	s_waitcnt vmcnt(8)
	s_waitcnt lgkmcnt(0)
	s_setprio 1
	s_barrier
	v_mfma_f32_16x16x32_bf16 v[128:131], v[144:147], v[182:185], v[128:131]
	v_mfma_f32_16x16x32_bf16 v[124:127], v[152:155], v[182:185], v[124:127]
	v_mfma_f32_16x16x32_bf16 v[120:123], v[144:147], v[190:193], v[120:123]
	v_mfma_f32_16x16x32_bf16 v[116:119], v[152:155], v[190:193], v[116:119]
	v_mfma_f32_16x16x32_bf16 v[112:115], v[144:147], v[198:201], v[112:115]
	v_mfma_f32_16x16x32_bf16 v[108:111], v[152:155], v[198:201], v[108:111]
	v_mfma_f32_16x16x32_bf16 v[104:107], v[144:147], v[206:209], v[104:107]
	v_mfma_f32_16x16x32_bf16 v[100:103], v[152:155], v[206:209], v[100:103]
	v_mfma_f32_16x16x32_bf16 v[128:131], v[148:151], v[186:189], v[128:131]
	v_mfma_f32_16x16x32_bf16 v[124:127], v[156:159], v[186:189], v[124:127]
	v_mfma_f32_16x16x32_bf16 v[120:123], v[148:151], v[194:197], v[120:123]
	v_mfma_f32_16x16x32_bf16 v[116:119], v[156:159], v[194:197], v[116:119]
	v_mfma_f32_16x16x32_bf16 v[112:115], v[148:151], v[202:205], v[112:115]
	v_mfma_f32_16x16x32_bf16 v[108:111], v[156:159], v[202:205], v[108:111]
	v_mfma_f32_16x16x32_bf16 v[104:107], v[148:151], v[220:223], v[104:107]
	v_mfma_f32_16x16x32_bf16 v[100:103], v[156:159], v[220:223], v[100:103]
	v_mfma_f32_16x16x32_bf16 v[96:99], v[160:163], v[182:185], v[96:99]
	v_mfma_f32_16x16x32_bf16 v[92:95], v[168:171], v[182:185], v[92:95]
	v_mfma_f32_16x16x32_bf16 v[88:91], v[160:163], v[190:193], v[88:91]
	v_mfma_f32_16x16x32_bf16 v[84:87], v[168:171], v[190:193], v[84:87]
	v_mfma_f32_16x16x32_bf16 v[80:83], v[160:163], v[198:201], v[80:83]
	v_mfma_f32_16x16x32_bf16 v[76:79], v[168:171], v[198:201], v[76:79]
	v_mfma_f32_16x16x32_bf16 v[72:75], v[160:163], v[206:209], v[72:75]
	v_mfma_f32_16x16x32_bf16 v[68:71], v[168:171], v[206:209], v[68:71]
	v_mfma_f32_16x16x32_bf16 v[96:99], v[164:167], v[186:189], v[96:99]
	v_mfma_f32_16x16x32_bf16 v[92:95], v[172:175], v[186:189], v[92:95]
	v_mfma_f32_16x16x32_bf16 v[88:91], v[164:167], v[194:197], v[88:91]
	v_mfma_f32_16x16x32_bf16 v[84:87], v[172:175], v[194:197], v[84:87]
	v_mfma_f32_16x16x32_bf16 v[80:83], v[164:167], v[202:205], v[80:83]
	v_mfma_f32_16x16x32_bf16 v[76:79], v[172:175], v[202:205], v[76:79]
	v_mfma_f32_16x16x32_bf16 v[72:75], v[164:167], v[220:223], v[72:75]
	v_mfma_f32_16x16x32_bf16 v[68:71], v[172:175], v[220:223], v[68:71]
	s_barrier
; #define PG8_STAGE(bufoff, gbase, voff) do { _Pragma("unroll") for (int _i = 0; _i < 2; ++_i) \
;         __builtin_amdgcn_global_load_lds((const unsigned*)((const char*)(gbase) + (voff)[_i]), (PG8_LAS unsigned*)(lds + (bufoff) + ldsw + _i * 8192), 16, 0, 0); } while (0)
; #define PG8_LDA(dst, b, h) do { _Pragma("unroll") for (int m = 0; m < 4; ++m) _Pragma("unroll") for (int k = 0; k < 2; ++k) dst[m][k] = *(const PG8_LAS bf16x8*)(lds + PG8_SA(b, h) + aoff + m * 2048 + k * 1024); } while (0)
; #define PG8_MMA(ai, bj, At, Bt) do { __builtin_amdgcn_s_setprio(1); _Pragma("unroll") for (int m = 0; m < 4; ++m) _Pragma("unroll") for (int n = 0; n < 2; ++n) _Pragma("unroll") for (int k = 0; k < 2; ++k) \
;         acc[ai][bj][m][n] = __builtin_amdgcn_mfma_f32_16x16x32_bf16(Bt[n][k], At[m][k], acc[ai][bj][m][n], 0, 0, 0); __builtin_amdgcn_s_setprio(0); } while (0)
; #define PG8_WAIT_V(n) asm volatile("s_waitcnt vmcnt(" #n ")" ::: "memory")
; #define PG8_WAIT_L(n) asm volatile("s_waitcnt lgkmcnt(" #n ")" ::: "memory")
; #define PG8_BAR __builtin_amdgcn_s_barrier()
; #define PG8_SCHED __builtin_amdgcn_sched_barrier(0)
; template <class Epi, class Sched, bool ALIGN_EPI = false, bool SP2 = false>
; __device__ __forceinline__ void gemm_phase(PG8_LAS unsigned char* lds, const Gemm g, const Sched& S, const Epi& E) {
;     ...
;             if (full) PG8_LDA(At, 1, 1); PG8_STAGE(PG8_SB(1, 0), b3, voffB); PG8_STAGE(PG8_SB(1, 1), b3 + hstep, voffB); PG8_STAGE(PG8_SA(1, 0), a3, voffA);
;             PG8_WAIT_V(8); PG8_WAIT_L(0); PG8_BAR; if (full) { PG8_MMA(1, 0, At, B0); PG8_MMA(1, 1, At, B1); } PG8_BAR; PG8_SCHED;
;     ...
;         if constexpr (ALIGN_EPI) { if (wr == 0) PG8_BAR; }
;         if constexpr (!Epi::AFTER_DRAIN) { E(acc, cur, wr, wc, fr, fq); S.done(cur); }
;         if (!has_next) break;
	s_setprio 0
	s_add_i32 s27, s27, s38
	v_lshl_add_u64 v[6:7], v[176:177], 0, s[52:53]
	s_mov_b32 m0, s27
	ds_read_b128 v[182:185], v181 offset:49152
	ds_read_b128 v[186:189], v181 offset:50176
	ds_read_b128 v[190:193], v181 offset:51200
	ds_read_b128 v[194:197], v181 offset:52224
	ds_read_b128 v[198:201], v181 offset:53248
	ds_read_b128 v[202:205], v181 offset:54272
	ds_read_b128 v[206:209], v181 offset:55296
	ds_read_b128 v[220:223], v181 offset:56320
	global_load_lds_dwordx4 v[6:7], off
	s_add_i32 m0, s27, 0x2000
	s_add_u32 s28, s28, 0x20080
	v_lshl_add_u64 v[6:7], v[210:211], 0, s[52:53]
	s_addc_u32 s29, s29, 0
	s_add_i32 s27, s54, s38
	global_load_lds_dwordx4 v[6:7], off
	v_lshl_add_u64 v[6:7], s[28:29], 0, v[134:135]
	s_mov_b32 m0, s27
	s_nop 0
	global_load_lds_dwordx4 v[6:7], off
	v_lshl_add_u64 v[6:7], s[28:29], 0, v[138:139]
	s_add_i32 m0, s27, 0x2000
	s_nop 0
	global_load_lds_dwordx4 v[6:7], off
	v_lshl_add_u64 v[6:7], v[212:213], 0, s[52:53]
	s_mov_b32 m0, s43
	s_nop 0
	global_load_lds_dwordx4 v[6:7], off
	v_lshl_add_u64 v[6:7], v[214:215], 0, s[52:53]
	s_mov_b32 m0, s44
	s_nop 0
	global_load_lds_dwordx4 v[6:7], off
	s_waitcnt vmcnt(8)
	s_waitcnt lgkmcnt(0)
	s_setprio 1
	s_barrier
	v_mfma_f32_16x16x32_bf16 v[64:67], v[144:147], v[182:185], v[64:67]
	v_mfma_f32_16x16x32_bf16 v[60:63], v[152:155], v[182:185], v[60:63]
	v_mfma_f32_16x16x32_bf16 v[56:59], v[144:147], v[190:193], v[56:59]
	v_mfma_f32_16x16x32_bf16 v[52:55], v[152:155], v[190:193], v[52:55]
	v_mfma_f32_16x16x32_bf16 v[48:51], v[144:147], v[198:201], v[48:51]
	v_mfma_f32_16x16x32_bf16 v[44:47], v[152:155], v[198:201], v[44:47]
	v_mfma_f32_16x16x32_bf16 v[40:43], v[144:147], v[206:209], v[40:43]
	v_mfma_f32_16x16x32_bf16 v[36:39], v[152:155], v[206:209], v[36:39]
	v_mfma_f32_16x16x32_bf16 v[64:67], v[148:151], v[186:189], v[64:67]
	v_mfma_f32_16x16x32_bf16 v[60:63], v[156:159], v[186:189], v[60:63]
	v_mfma_f32_16x16x32_bf16 v[56:59], v[148:151], v[194:197], v[56:59]
	v_mfma_f32_16x16x32_bf16 v[52:55], v[156:159], v[194:197], v[52:55]
	v_mfma_f32_16x16x32_bf16 v[48:51], v[148:151], v[202:205], v[48:51]
	v_mfma_f32_16x16x32_bf16 v[44:47], v[156:159], v[202:205], v[44:47]
	v_mfma_f32_16x16x32_bf16 v[40:43], v[148:151], v[220:223], v[40:43]
	v_mfma_f32_16x16x32_bf16 v[36:39], v[156:159], v[220:223], v[36:39]
	v_mfma_f32_16x16x32_bf16 v[32:35], v[160:163], v[182:185], v[32:35]
	v_mfma_f32_16x16x32_bf16 v[28:31], v[168:171], v[182:185], v[28:31]
	v_mfma_f32_16x16x32_bf16 v[24:27], v[160:163], v[190:193], v[24:27]
	v_mfma_f32_16x16x32_bf16 v[20:23], v[168:171], v[190:193], v[20:23]
	v_mfma_f32_16x16x32_bf16 v[16:19], v[160:163], v[198:201], v[16:19]
	v_mfma_f32_16x16x32_bf16 v[12:15], v[168:171], v[198:201], v[12:15]
	v_mfma_f32_16x16x32_bf16 v[6:9], v[160:163], v[206:209], v[8:11]
	v_mfma_f32_16x16x32_bf16 v[2:5], v[168:171], v[206:209], v[2:5]
	v_mfma_f32_16x16x32_bf16 v[32:35], v[164:167], v[186:189], v[32:35]
	v_mfma_f32_16x16x32_bf16 v[28:31], v[172:175], v[186:189], v[28:31]
	v_mfma_f32_16x16x32_bf16 v[24:27], v[164:167], v[194:197], v[24:27]
	v_mfma_f32_16x16x32_bf16 v[20:23], v[172:175], v[194:197], v[20:23]
	v_mfma_f32_16x16x32_bf16 v[16:19], v[164:167], v[202:205], v[16:19]
	v_mfma_f32_16x16x32_bf16 v[12:15], v[172:175], v[202:205], v[12:15]
	v_mfma_f32_16x16x32_bf16 v[8:11], v[164:167], v[220:223], v[6:9]
	v_mfma_f32_16x16x32_bf16 v[4:7], v[172:175], v[220:223], v[2:5]
	s_barrier
	s_setprio 0
	s_add_i32 s25, s25, 2
	s_add_u32 s6, s6, 0x100
	s_addc_u32 s7, s7, 0
	s_add_u32 s17, s17, 0x100
	s_addc_u32 s19, s19, 0
	s_cmp_gt_u32 s25, 5
	s_cbranch_scc0 .LBB0_1038
	s_and_b64 vcc, exec, s[14:15]
	s_cbranch_vccz .LBB0_1041
	s_barrier

; #define PG8_STAGE(bufoff, gbase, voff) do { _Pragma("unroll") for (int _i = 0; _i < 2; ++_i) \
;         __builtin_amdgcn_global_load_lds((const unsigned*)((const char*)(gbase) + (voff)[_i]), (PG8_LAS unsigned*)(lds + (bufoff) + ldsw + _i * 8192), 16, 0, 0); } while (0)
; #define PG8_LDA(dst, b, h) do { _Pragma("unroll") for (int m = 0; m < 4; ++m) _Pragma("unroll") for (int k = 0; k < 2; ++k) dst[m][k] = *(const PG8_LAS bf16x8*)(lds + PG8_SA(b, h) + aoff + m * 2048 + k * 1024); } while (0)
; #define PG8_LDB(dst, b, h) do { _Pragma("unroll") for (int n = 0; n < 2; ++n) _Pragma("unroll") for (int k = 0; k < 2; ++k) dst[n][k] = *(const PG8_LAS bf16x8*)(lds + PG8_SB(b, h) + boff + n * 2048 + k * 1024); } while (0)
; #define PG8_MMA(ai, bj, At, Bt) do { __builtin_amdgcn_s_setprio(1); _Pragma("unroll") for (int m = 0; m < 4; ++m) _Pragma("unroll") for (int n = 0; n < 2; ++n) _Pragma("unroll") for (int k = 0; k < 2; ++k) \
;         acc[ai][bj][m][n] = __builtin_amdgcn_mfma_f32_16x16x32_bf16(Bt[n][k], At[m][k], acc[ai][bj][m][n], 0, 0, 0); __builtin_amdgcn_s_setprio(0); } while (0)
; #define PG8_WAIT_V(n) asm volatile("s_waitcnt vmcnt(" #n ")" ::: "memory")
; #define PG8_BAR __builtin_amdgcn_s_barrier()
; template <class Epi, class Sched, bool ALIGN_EPI = false, bool SP2 = false>
; __device__ __forceinline__ void gemm_phase(PG8_LAS unsigned char* lds, const Gemm g, const Sched& S, const Epi& E) {
;     ...
;         for (int t = 0; t < nt; t += 2) {
;             const bool last = (t == nt - 2);
;             const char* a1 = cA + (size_t)(t + 1) * kstep;
;             const char* a2 = last ? nA : cA + (size_t)(t + 2) * kstep; const char* b2 = last ? nB : cB + (size_t)(t + 2) * kstep;
;             const char* a3 = a2 + kstep; const char* b3 = b2 + kstep;
;             if (last && has_next) S.a_ready(nxt);
;             if constexpr (SP2) {
;             PG8_LDB(B0, 0, 0); PG8_LDB(B1, 0, 1); PG8_SCHED; PG8_LDA(At, 0, 0); PG8_STAGE(PG8_SA(1, 1), a1 + hstep, voffA);
;             PG8_WAIT_V(8); PG8_WAIT_L(0); PG8_BAR; PG8_MMA(0, 0, At, B0); PG8_MMA(0, 1, At, B1); PG8_BAR; PG8_SCHED;
;             if (full) PG8_LDA(At, 0, 1); PG8_STAGE(PG8_SB(0, 0), b2, voffB); PG8_STAGE(PG8_SB(0, 1), b2 + hstep, voffB); PG8_STAGE(PG8_SA(0, 0), a2, voffA);
;             PG8_WAIT_V(8); PG8_WAIT_L(0); PG8_BAR; if (full) { PG8_MMA(1, 0, At, B0); PG8_MMA(1, 1, At, B1); } PG8_BAR; PG8_SCHED;
.LBB0_1149:
	s_add_u32 s30, s18, s28
	s_addc_u32 s31, s19, s29
	s_add_u32 s30, s30, 0x100
	s_addc_u32 s31, s31, 0
	s_add_u32 s62, s57, s28
	s_addc_u32 s63, s58, s29
	s_add_i32 s64, 0, 0x10000
	s_cmpk_eq_i32 s28, 0x700
	s_cselect_b32 s35, s23, s31
	s_cselect_b32 s34, s59, s30
	v_add_u32_e32 v143, s64, v140
	s_cselect_b32 s31, s21, s63
	s_cselect_b32 s30, s60, s62
	s_add_i32 s65, 0, 0x14000
	ds_read_b128 v[144:147], v143
	ds_read_b128 v[148:151], v143 offset:1024
	ds_read_b128 v[152:155], v143 offset:2048
	ds_read_b128 v[156:159], v143 offset:3072
	v_add_u32_e32 v143, s65, v140
	ds_read_b128 v[160:163], v143
	ds_read_b128 v[164:167], v143 offset:1024
	ds_read_b128 v[168:171], v143 offset:2048
	ds_read_b128 v[174:177], v143 offset:3072
	v_lshl_add_u64 v[210:211], v[136:137], 0, s[28:29]
	s_add_i32 m0, s41, 0xc000
	ds_read_b128 v[178:181], v141
	ds_read_b128 v[182:185], v141 offset:1024
	ds_read_b128 v[186:189], v141 offset:2048
	ds_read_b128 v[190:193], v141 offset:3072
	ds_read_b128 v[194:197], v141 offset:4096
	ds_read_b128 v[198:201], v141 offset:5120
	ds_read_b128 v[202:205], v141 offset:6144
	ds_read_b128 v[206:209], v141 offset:7168
	global_load_lds_dwordx4 v[210:211], off
	v_lshl_add_u64 v[210:211], v[138:139], 0, s[28:29]
	s_add_i32 m0, s41, 0xe000
	s_nop 0
	global_load_lds_dwordx4 v[210:211], off
	s_waitcnt vmcnt(8)
	s_waitcnt lgkmcnt(0)
	s_setprio 1
	s_barrier
	v_mfma_f32_16x16x32_bf16 v[126:129], v[144:147], v[178:181], v[126:129]
	v_mfma_f32_16x16x32_bf16 v[86:89], v[152:155], v[178:181], v[86:89]
	v_mfma_f32_16x16x32_bf16 v[114:117], v[144:147], v[186:189], v[114:117]
	v_mfma_f32_16x16x32_bf16 v[82:85], v[152:155], v[186:189], v[82:85]
	v_mfma_f32_16x16x32_bf16 v[122:125], v[144:147], v[194:197], v[122:125]
	v_mfma_f32_16x16x32_bf16 v[106:109], v[152:155], v[194:197], v[106:109]
	v_mfma_f32_16x16x32_bf16 v[118:121], v[144:147], v[202:205], v[118:121]
	v_mfma_f32_16x16x32_bf16 v[110:113], v[152:155], v[202:205], v[110:113]
	v_mfma_f32_16x16x32_bf16 v[126:129], v[148:151], v[182:185], v[126:129]
	v_mfma_f32_16x16x32_bf16 v[86:89], v[156:159], v[182:185], v[86:89]
	v_mfma_f32_16x16x32_bf16 v[114:117], v[148:151], v[190:193], v[114:117]
	v_mfma_f32_16x16x32_bf16 v[82:85], v[156:159], v[190:193], v[82:85]
	v_mfma_f32_16x16x32_bf16 v[122:125], v[148:151], v[198:201], v[122:125]
	v_mfma_f32_16x16x32_bf16 v[106:109], v[156:159], v[198:201], v[106:109]
	v_mfma_f32_16x16x32_bf16 v[118:121], v[148:151], v[206:209], v[118:121]
	v_mfma_f32_16x16x32_bf16 v[110:113], v[156:159], v[206:209], v[110:113]
	v_mfma_f32_16x16x32_bf16 v[22:25], v[160:163], v[178:181], v[22:25]
	v_mfma_f32_16x16x32_bf16 v[6:9], v[168:171], v[178:181], v[6:9]
	v_mfma_f32_16x16x32_bf16 v[18:21], v[160:163], v[186:189], v[18:21]
	v_mfma_f32_16x16x32_bf16 v[2:5], v[168:171], v[186:189], v[2:5]
	v_mfma_f32_16x16x32_bf16 v[38:41], v[160:163], v[194:197], v[38:41]
	v_mfma_f32_16x16x32_bf16 v[10:13], v[168:171], v[194:197], v[10:13]
	v_mfma_f32_16x16x32_bf16 v[34:37], v[160:163], v[202:205], v[34:37]
	v_mfma_f32_16x16x32_bf16 v[14:17], v[168:171], v[202:205], v[14:17]
	v_mfma_f32_16x16x32_bf16 v[22:25], v[164:167], v[182:185], v[22:25]
	v_mfma_f32_16x16x32_bf16 v[6:9], v[174:177], v[182:185], v[6:9]
	v_mfma_f32_16x16x32_bf16 v[18:21], v[164:167], v[190:193], v[18:21]
	v_mfma_f32_16x16x32_bf16 v[2:5], v[174:177], v[190:193], v[2:5]
	v_mfma_f32_16x16x32_bf16 v[38:41], v[164:167], v[198:201], v[38:41]
	v_mfma_f32_16x16x32_bf16 v[10:13], v[174:177], v[198:201], v[10:13]
	v_mfma_f32_16x16x32_bf16 v[34:37], v[164:167], v[206:209], v[34:37]
	v_mfma_f32_16x16x32_bf16 v[14:17], v[174:177], v[206:209], v[14:17]
	s_barrier
	s_setprio 0
	s_add_i32 s62, s64, s40
	v_lshl_add_u64 v[210:211], s[30:31], 0, v[0:1]
	s_mov_b32 m0, s62
	ds_read_b128 v[178:181], v141 offset:16384
	ds_read_b128 v[182:185], v141 offset:17408
	ds_read_b128 v[186:189], v141 offset:18432
	ds_read_b128 v[190:193], v141 offset:19456
	ds_read_b128 v[194:197], v141 offset:20480
	ds_read_b128 v[198:201], v141 offset:21504
	ds_read_b128 v[202:205], v141 offset:22528
	ds_read_b128 v[206:209], v141 offset:23552
	global_load_lds_dwordx4 v[210:211], off
	s_add_i32 m0, s62, 0x2000
	s_add_u32 s62, s30, 0x40000
	v_lshl_add_u64 v[212:213], s[30:31], 0, v[130:131]
	s_addc_u32 s63, s31, 0
	s_add_i32 s64, s65, s40
	global_load_lds_dwordx4 v[212:213], off
	v_lshl_add_u64 v[214:215], s[62:63], 0, v[0:1]
	s_mov_b32 m0, s64
	v_lshl_add_u64 v[220:221], s[34:35], 0, v[130:131]
	global_load_lds_dwordx4 v[214:215], off
	v_lshl_add_u64 v[214:215], s[62:63], 0, v[130:131]
	s_add_i32 m0, s64, 0x2000
	s_nop 0
	global_load_lds_dwordx4 v[214:215], off
	v_lshl_add_u64 v[214:215], s[34:35], 0, v[0:1]
	s_mov_b32 m0, s41
	s_nop 0
	global_load_lds_dwordx4 v[214:215], off
	s_mov_b32 m0, s42
	s_nop 0
	global_load_lds_dwordx4 v[220:221], off
	s_waitcnt vmcnt(8)
	s_waitcnt lgkmcnt(0)
	s_setprio 1
	s_barrier
; #define PG8_STAGE(bufoff, gbase, voff) do { _Pragma("unroll") for (int _i = 0; _i < 2; ++_i) \
;         __builtin_amdgcn_global_load_lds((const unsigned*)((const char*)(gbase) + (voff)[_i]), (PG8_LAS unsigned*)(lds + (bufoff) + ldsw + _i * 8192), 16, 0, 0); } while (0)
; #define PG8_LDA(dst, b, h) do { _Pragma("unroll") for (int m = 0; m < 4; ++m) _Pragma("unroll") for (int k = 0; k < 2; ++k) dst[m][k] = *(const PG8_LAS bf16x8*)(lds + PG8_SA(b, h) + aoff + m * 2048 + k * 1024); } while (0)
; #define PG8_LDB(dst, b, h) do { _Pragma("unroll") for (int n = 0; n < 2; ++n) _Pragma("unroll") for (int k = 0; k < 2; ++k) dst[n][k] = *(const PG8_LAS bf16x8*)(lds + PG8_SB(b, h) + boff + n * 2048 + k * 1024); } while (0)
; #define PG8_MMA(ai, bj, At, Bt) do { __builtin_amdgcn_s_setprio(1); _Pragma("unroll") for (int m = 0; m < 4; ++m) _Pragma("unroll") for (int n = 0; n < 2; ++n) _Pragma("unroll") for (int k = 0; k < 2; ++k) \
;         acc[ai][bj][m][n] = __builtin_amdgcn_mfma_f32_16x16x32_bf16(Bt[n][k], At[m][k], acc[ai][bj][m][n], 0, 0, 0); __builtin_amdgcn_s_setprio(0); } while (0)
; #define PG8_WAIT_V(n) asm volatile("s_waitcnt vmcnt(" #n ")" ::: "memory")
; #define PG8_WAIT_L(n) asm volatile("s_waitcnt lgkmcnt(" #n ")" ::: "memory")
; #define PG8_BAR __builtin_amdgcn_s_barrier()
; #define PG8_SCHED __builtin_amdgcn_sched_barrier(0)
; template <class Epi, class Sched, bool ALIGN_EPI = false, bool SP2 = false>
; __device__ __forceinline__ void gemm_phase(PG8_LAS unsigned char* lds, const Gemm g, const Sched& S, const Epi& E) {
;     ...
;             PG8_WAIT_V(8); PG8_WAIT_L(0); PG8_BAR; if (full) { PG8_MMA(1, 0, At, B0); PG8_MMA(1, 1, At, B1); } PG8_BAR; PG8_SCHED;
;             PG8_LDB(B0, 1, 0); PG8_LDB(B1, 1, 1); PG8_SCHED; PG8_LDA(At, 1, 0); PG8_STAGE(PG8_SA(0, 1), a2 + hstep, voffA);
;             PG8_WAIT_V(8); PG8_WAIT_L(0); PG8_BAR; PG8_MMA(0, 0, At, B0); PG8_MMA(0, 1, At, B1); PG8_BAR; PG8_SCHED;
	v_mfma_f32_16x16x32_bf16 v[102:105], v[144:147], v[178:181], v[102:105]
	v_mfma_f32_16x16x32_bf16 v[98:101], v[152:155], v[178:181], v[98:101]
	v_mfma_f32_16x16x32_bf16 v[94:97], v[144:147], v[186:189], v[94:97]
	v_mfma_f32_16x16x32_bf16 v[90:93], v[152:155], v[186:189], v[90:93]
	v_mfma_f32_16x16x32_bf16 v[78:81], v[144:147], v[194:197], v[78:81]
	v_mfma_f32_16x16x32_bf16 v[74:77], v[152:155], v[194:197], v[74:77]
	v_mfma_f32_16x16x32_bf16 v[70:73], v[144:147], v[202:205], v[70:73]
	v_mfma_f32_16x16x32_bf16 v[66:69], v[152:155], v[202:205], v[66:69]
	v_mfma_f32_16x16x32_bf16 v[102:105], v[148:151], v[182:185], v[102:105]
	v_mfma_f32_16x16x32_bf16 v[98:101], v[156:159], v[182:185], v[98:101]
	v_mfma_f32_16x16x32_bf16 v[94:97], v[148:151], v[190:193], v[94:97]
	v_mfma_f32_16x16x32_bf16 v[90:93], v[156:159], v[190:193], v[90:93]
	v_mfma_f32_16x16x32_bf16 v[78:81], v[148:151], v[198:201], v[78:81]
	v_mfma_f32_16x16x32_bf16 v[74:77], v[156:159], v[198:201], v[74:77]
	v_mfma_f32_16x16x32_bf16 v[70:73], v[148:151], v[206:209], v[70:73]
	v_mfma_f32_16x16x32_bf16 v[66:69], v[156:159], v[206:209], v[66:69]
	v_mfma_f32_16x16x32_bf16 v[50:53], v[160:163], v[178:181], v[50:53]
	v_mfma_f32_16x16x32_bf16 v[26:29], v[168:171], v[178:181], v[26:29]
	v_mfma_f32_16x16x32_bf16 v[46:49], v[160:163], v[186:189], v[46:49]
	v_mfma_f32_16x16x32_bf16 v[30:33], v[168:171], v[186:189], v[30:33]
	v_mfma_f32_16x16x32_bf16 v[62:65], v[160:163], v[194:197], v[62:65]
	v_mfma_f32_16x16x32_bf16 v[54:57], v[168:171], v[194:197], v[54:57]
	v_mfma_f32_16x16x32_bf16 v[58:61], v[160:163], v[202:205], v[58:61]
	v_mfma_f32_16x16x32_bf16 v[42:45], v[168:171], v[202:205], v[42:45]
	v_mfma_f32_16x16x32_bf16 v[50:53], v[164:167], v[182:185], v[50:53]
	v_mfma_f32_16x16x32_bf16 v[26:29], v[174:177], v[182:185], v[26:29]
	v_mfma_f32_16x16x32_bf16 v[46:49], v[164:167], v[190:193], v[46:49]
	v_mfma_f32_16x16x32_bf16 v[30:33], v[174:177], v[190:193], v[30:33]
	v_mfma_f32_16x16x32_bf16 v[62:65], v[164:167], v[198:201], v[62:65]
	v_mfma_f32_16x16x32_bf16 v[54:57], v[174:177], v[198:201], v[54:57]
	v_mfma_f32_16x16x32_bf16 v[58:61], v[164:167], v[206:209], v[58:61]
	v_mfma_f32_16x16x32_bf16 v[42:45], v[174:177], v[206:209], v[42:45]
	s_barrier
	s_setprio 0
	s_add_i32 s62, 0, 0x18000
	v_add_u32_e32 v143, s62, v140
	s_add_i32 s63, 0, 0x1c000
	ds_read_b128 v[144:147], v143
	ds_read_b128 v[148:151], v143 offset:1024
	ds_read_b128 v[152:155], v143 offset:2048
	ds_read_b128 v[156:159], v143 offset:3072
	v_add_u32_e32 v143, s63, v140
	ds_read_b128 v[160:163], v143
	ds_read_b128 v[164:167], v143 offset:1024
	ds_read_b128 v[168:171], v143 offset:2048
	ds_read_b128 v[174:177], v143 offset:3072
	s_add_u32 s34, s34, 0x40000
	s_addc_u32 s35, s35, 0
	s_mov_b32 m0, s43
	v_lshl_add_u64 v[222:223], s[34:35], 0, v[0:1]
	ds_read_b128 v[178:181], v141 offset:32768
	ds_read_b128 v[182:185], v141 offset:33792
	ds_read_b128 v[186:189], v141 offset:34816
	ds_read_b128 v[190:193], v141 offset:35840
	ds_read_b128 v[194:197], v141 offset:36864
	ds_read_b128 v[198:201], v141 offset:37888
	ds_read_b128 v[202:205], v141 offset:38912
	ds_read_b128 v[206:209], v141 offset:39936
	global_load_lds_dwordx4 v[222:223], off
	v_lshl_add_u64 v[222:223], s[34:35], 0, v[130:131]
	s_mov_b32 m0, s44
	s_nop 0
	global_load_lds_dwordx4 v[222:223], off
	s_waitcnt vmcnt(8)
	s_waitcnt lgkmcnt(0)
	s_setprio 1
	s_barrier
	v_mfma_f32_16x16x32_bf16 v[126:129], v[144:147], v[178:181], v[126:129]
	v_mfma_f32_16x16x32_bf16 v[86:89], v[152:155], v[178:181], v[86:89]
	v_mfma_f32_16x16x32_bf16 v[114:117], v[144:147], v[186:189], v[114:117]
	v_mfma_f32_16x16x32_bf16 v[82:85], v[152:155], v[186:189], v[82:85]
	v_mfma_f32_16x16x32_bf16 v[122:125], v[144:147], v[194:197], v[122:125]
	v_mfma_f32_16x16x32_bf16 v[106:109], v[152:155], v[194:197], v[106:109]
	v_mfma_f32_16x16x32_bf16 v[118:121], v[144:147], v[202:205], v[118:121]
	v_mfma_f32_16x16x32_bf16 v[110:113], v[152:155], v[202:205], v[110:113]
	v_mfma_f32_16x16x32_bf16 v[126:129], v[148:151], v[182:185], v[126:129]
	v_mfma_f32_16x16x32_bf16 v[86:89], v[156:159], v[182:185], v[86:89]
	v_mfma_f32_16x16x32_bf16 v[114:117], v[148:151], v[190:193], v[114:117]
	v_mfma_f32_16x16x32_bf16 v[82:85], v[156:159], v[190:193], v[82:85]
	v_mfma_f32_16x16x32_bf16 v[122:125], v[148:151], v[198:201], v[122:125]
	v_mfma_f32_16x16x32_bf16 v[106:109], v[156:159], v[198:201], v[106:109]
	v_mfma_f32_16x16x32_bf16 v[118:121], v[148:151], v[206:209], v[118:121]
	v_mfma_f32_16x16x32_bf16 v[110:113], v[156:159], v[206:209], v[110:113]
	v_mfma_f32_16x16x32_bf16 v[22:25], v[160:163], v[178:181], v[22:25]
	v_mfma_f32_16x16x32_bf16 v[6:9], v[168:171], v[178:181], v[6:9]
	v_mfma_f32_16x16x32_bf16 v[18:21], v[160:163], v[186:189], v[18:21]
	v_mfma_f32_16x16x32_bf16 v[2:5], v[168:171], v[186:189], v[2:5]
	v_mfma_f32_16x16x32_bf16 v[38:41], v[160:163], v[194:197], v[38:41]
	v_mfma_f32_16x16x32_bf16 v[10:13], v[168:171], v[194:197], v[10:13]
	v_mfma_f32_16x16x32_bf16 v[34:37], v[160:163], v[202:205], v[34:37]
	v_mfma_f32_16x16x32_bf16 v[14:17], v[168:171], v[202:205], v[14:17]
	v_mfma_f32_16x16x32_bf16 v[22:25], v[164:167], v[182:185], v[22:25]
	v_mfma_f32_16x16x32_bf16 v[6:9], v[174:177], v[182:185], v[6:9]
	v_mfma_f32_16x16x32_bf16 v[18:21], v[164:167], v[190:193], v[18:21]
	v_mfma_f32_16x16x32_bf16 v[2:5], v[174:177], v[190:193], v[2:5]
	v_mfma_f32_16x16x32_bf16 v[38:41], v[164:167], v[198:201], v[38:41]
	v_mfma_f32_16x16x32_bf16 v[10:13], v[174:177], v[198:201], v[10:13]
	v_mfma_f32_16x16x32_bf16 v[34:37], v[164:167], v[206:209], v[34:37]
	v_mfma_f32_16x16x32_bf16 v[14:17], v[174:177], v[206:209], v[14:17]
	s_barrier
; #define PG8_STAGE(bufoff, gbase, voff) do { _Pragma("unroll") for (int _i = 0; _i < 2; ++_i) \
;         __builtin_amdgcn_global_load_lds((const unsigned*)((const char*)(gbase) + (voff)[_i]), (PG8_LAS unsigned*)(lds + (bufoff) + ldsw + _i * 8192), 16, 0, 0); } while (0)
; #define PG8_LDA(dst, b, h) do { _Pragma("unroll") for (int m = 0; m < 4; ++m) _Pragma("unroll") for (int k = 0; k < 2; ++k) dst[m][k] = *(const PG8_LAS bf16x8*)(lds + PG8_SA(b, h) + aoff + m * 2048 + k * 1024); } while (0)
; #define PG8_MMA(ai, bj, At, Bt) do { __builtin_amdgcn_s_setprio(1); _Pragma("unroll") for (int m = 0; m < 4; ++m) _Pragma("unroll") for (int n = 0; n < 2; ++n) _Pragma("unroll") for (int k = 0; k < 2; ++k) \
;         acc[ai][bj][m][n] = __builtin_amdgcn_mfma_f32_16x16x32_bf16(Bt[n][k], At[m][k], acc[ai][bj][m][n], 0, 0, 0); __builtin_amdgcn_s_setprio(0); } while (0)
; #define PG8_WAIT_V(n) asm volatile("s_waitcnt vmcnt(" #n ")" ::: "memory")
; #define PG8_WAIT_L(n) asm volatile("s_waitcnt lgkmcnt(" #n ")" ::: "memory")
; #define PG8_BAR __builtin_amdgcn_s_barrier()
; #define PG8_SCHED __builtin_amdgcn_sched_barrier(0)
; template <class Epi, class Sched, bool ALIGN_EPI = false, bool SP2 = false>
; __device__ __forceinline__ void gemm_phase(PG8_LAS unsigned char* lds, const Gemm g, const Sched& S, const Epi& E) {
;     ...
;             if (full) PG8_LDA(At, 1, 1); PG8_STAGE(PG8_SB(1, 0), b3, voffB); PG8_STAGE(PG8_SB(1, 1), b3 + hstep, voffB); PG8_STAGE(PG8_SA(1, 0), a3, voffA);
;             PG8_WAIT_V(8); PG8_WAIT_L(0); PG8_BAR; if (full) { PG8_MMA(1, 0, At, B0); PG8_MMA(1, 1, At, B1); } PG8_BAR; PG8_SCHED;
;     ...
;         if (!has_next) break;
;         if (!Sched::KEEP || (nxt.pn >> 2) == 0) {
; #pragma unroll
;         for (int a = 0; a < 2; ++a)
; #pragma unroll
;             for (int b = 0; b < 2; ++b)
; #pragma unroll
;                 for (int m = 0; m < 4; ++m)
; #pragma unroll
;                     for (int n = 0; n < 2; ++n) acc[a][b][m][n] = (f32x4){0.f, 0.f, 0.f, 0.f};
;         }
;         cur = nxt; cA = nA; cB = nB; ++ui;
	s_setprio 0
	s_add_i32 s34, s62, s40
	v_lshl_add_u64 v[210:211], v[210:211], 0, s[52:53]
	s_mov_b32 m0, s34
	ds_read_b128 v[178:181], v141 offset:49152
	ds_read_b128 v[182:185], v141 offset:50176
	ds_read_b128 v[186:189], v141 offset:51200
	ds_read_b128 v[190:193], v141 offset:52224
	ds_read_b128 v[194:197], v141 offset:53248
	ds_read_b128 v[198:201], v141 offset:54272
	ds_read_b128 v[202:205], v141 offset:55296
	ds_read_b128 v[206:209], v141 offset:56320
	global_load_lds_dwordx4 v[210:211], off
	s_add_i32 m0, s34, 0x2000
	s_add_u32 s30, s30, 0x40080
	v_lshl_add_u64 v[210:211], v[212:213], 0, s[52:53]
	s_addc_u32 s31, s31, 0
	s_add_i32 s34, s63, s40
	global_load_lds_dwordx4 v[210:211], off
	v_lshl_add_u64 v[210:211], s[30:31], 0, v[0:1]
	s_mov_b32 m0, s34
	s_nop 0
	global_load_lds_dwordx4 v[210:211], off
	v_lshl_add_u64 v[210:211], s[30:31], 0, v[130:131]
	s_add_i32 m0, s34, 0x2000
	s_nop 0
	global_load_lds_dwordx4 v[210:211], off
	v_lshl_add_u64 v[210:211], v[214:215], 0, s[52:53]
	s_mov_b32 m0, s48
	s_nop 0
	global_load_lds_dwordx4 v[210:211], off
	v_lshl_add_u64 v[210:211], v[220:221], 0, s[52:53]
	s_mov_b32 m0, s49
	s_nop 0
	global_load_lds_dwordx4 v[210:211], off
	s_waitcnt vmcnt(8)
	s_waitcnt lgkmcnt(0)
	s_setprio 1
	s_barrier
	v_mfma_f32_16x16x32_bf16 v[102:105], v[144:147], v[178:181], v[102:105]
	v_mfma_f32_16x16x32_bf16 v[98:101], v[152:155], v[178:181], v[98:101]
	v_mfma_f32_16x16x32_bf16 v[94:97], v[144:147], v[186:189], v[94:97]
	v_mfma_f32_16x16x32_bf16 v[90:93], v[152:155], v[186:189], v[90:93]
	v_mfma_f32_16x16x32_bf16 v[78:81], v[144:147], v[194:197], v[78:81]
	v_mfma_f32_16x16x32_bf16 v[74:77], v[152:155], v[194:197], v[74:77]
	v_mfma_f32_16x16x32_bf16 v[70:73], v[144:147], v[202:205], v[70:73]
	v_mfma_f32_16x16x32_bf16 v[66:69], v[152:155], v[202:205], v[66:69]
	v_mfma_f32_16x16x32_bf16 v[102:105], v[148:151], v[182:185], v[102:105]
	v_mfma_f32_16x16x32_bf16 v[98:101], v[156:159], v[182:185], v[98:101]
	v_mfma_f32_16x16x32_bf16 v[94:97], v[148:151], v[190:193], v[94:97]
	v_mfma_f32_16x16x32_bf16 v[90:93], v[156:159], v[190:193], v[90:93]
	v_mfma_f32_16x16x32_bf16 v[78:81], v[148:151], v[198:201], v[78:81]
	v_mfma_f32_16x16x32_bf16 v[74:77], v[156:159], v[198:201], v[74:77]
	v_mfma_f32_16x16x32_bf16 v[70:73], v[148:151], v[206:209], v[70:73]
	v_mfma_f32_16x16x32_bf16 v[66:69], v[156:159], v[206:209], v[66:69]
	v_mfma_f32_16x16x32_bf16 v[50:53], v[160:163], v[178:181], v[50:53]
	v_mfma_f32_16x16x32_bf16 v[26:29], v[168:171], v[178:181], v[26:29]
	v_mfma_f32_16x16x32_bf16 v[46:49], v[160:163], v[186:189], v[46:49]
	v_mfma_f32_16x16x32_bf16 v[30:33], v[168:171], v[186:189], v[30:33]
	v_mfma_f32_16x16x32_bf16 v[62:65], v[160:163], v[194:197], v[62:65]
	v_mfma_f32_16x16x32_bf16 v[54:57], v[168:171], v[194:197], v[54:57]
	v_mfma_f32_16x16x32_bf16 v[58:61], v[160:163], v[202:205], v[58:61]
	v_mfma_f32_16x16x32_bf16 v[42:45], v[168:171], v[202:205], v[42:45]
	v_mfma_f32_16x16x32_bf16 v[50:53], v[164:167], v[182:185], v[50:53]
	v_mfma_f32_16x16x32_bf16 v[26:29], v[174:177], v[182:185], v[26:29]
	v_mfma_f32_16x16x32_bf16 v[46:49], v[164:167], v[190:193], v[46:49]
	v_mfma_f32_16x16x32_bf16 v[30:33], v[174:177], v[190:193], v[30:33]
	v_mfma_f32_16x16x32_bf16 v[62:65], v[164:167], v[198:201], v[62:65]
	v_mfma_f32_16x16x32_bf16 v[54:57], v[174:177], v[198:201], v[54:57]
	v_mfma_f32_16x16x32_bf16 v[58:61], v[164:167], v[206:209], v[58:61]
	v_mfma_f32_16x16x32_bf16 v[42:45], v[174:177], v[206:209], v[42:45]
	s_barrier
	s_setprio 0
	s_add_i32 s61, s61, 2
	s_add_u32 s28, s28, 0x100
	s_addc_u32 s29, s29, 0
	s_cmp_gt_u32 s61, 13
	s_cbranch_scc0 .LBB0_1149
	s_add_u32 s28, s57, 0xffffff00
	s_addc_u32 s29, s58, -1
	s_andn2_b64 vcc, exec, s[6:7]
	s_cbranch_vccnz .LBB0_1152
	v_mov_b32_e32 v42, 0
	s_mov_b32 s14, s20
	s_mov_b32 s12, s22
	s_mov_b64 s[18:19], s[26:27]
	s_mov_b32 s55, s56
	v_mov_b32_e32 v43, v42
	v_mov_b32_e32 v44, v42
	v_mov_b32_e32 v45, v42
	v_mov_b32_e32 v58, v42
	v_mov_b32_e32 v59, v42
	v_mov_b32_e32 v60, v42
	v_mov_b32_e32 v61, v42
	v_mov_b32_e32 v54, v42
	v_mov_b32_e32 v55, v42
	v_mov_b32_e32 v56, v42
	v_mov_b32_e32 v57, v42
	v_mov_b32_e32 v62, v42
	v_mov_b32_e32 v63, v42
	v_mov_b32_e32 v64, v42
	v_mov_b32_e32 v65, v42
	v_mov_b32_e32 v30, v42
	v_mov_b32_e32 v31, v42
	v_mov_b32_e32 v32, v42
	v_mov_b32_e32 v33, v42
	v_mov_b32_e32 v46, v42
	v_mov_b32_e32 v47, v42
	v_mov_b32_e32 v48, v42
	v_mov_b32_e32 v49, v42
	v_mov_b32_e32 v26, v42
	v_mov_b32_e32 v27, v42
	v_mov_b32_e32 v28, v42
	v_mov_b32_e32 v29, v42
	v_mov_b32_e32 v50, v42
	v_mov_b32_e32 v51, v42
	v_mov_b32_e32 v52, v42
	v_mov_b32_e32 v53, v42
	v_mov_b32_e32 v66, v42
	v_mov_b32_e32 v67, v42
	v_mov_b32_e32 v68, v42
	v_mov_b32_e32 v69, v42
	v_mov_b32_e32 v70, v42
	v_mov_b32_e32 v71, v42
	v_mov_b32_e32 v72, v42
	v_mov_b32_e32 v73, v42
	v_mov_b32_e32 v74, v42
	v_mov_b32_e32 v75, v42
	v_mov_b32_e32 v76, v42
	v_mov_b32_e32 v77, v42
	v_mov_b32_e32 v78, v42
	v_mov_b32_e32 v79, v42
	v_mov_b32_e32 v80, v42
	v_mov_b32_e32 v81, v42
	v_mov_b32_e32 v90, v42
	v_mov_b32_e32 v91, v42
	v_mov_b32_e32 v92, v42
	v_mov_b32_e32 v93, v42
	v_mov_b32_e32 v94, v42
	v_mov_b32_e32 v95, v42
	v_mov_b32_e32 v96, v42
	v_mov_b32_e32 v97, v42
	v_mov_b32_e32 v98, v42
	v_mov_b32_e32 v99, v42
	v_mov_b32_e32 v100, v42
	v_mov_b32_e32 v101, v42
	v_mov_b32_e32 v102, v42
	v_mov_b32_e32 v103, v42
	v_mov_b32_e32 v104, v42
	v_mov_b32_e32 v105, v42
	v_mov_b32_e32 v14, v42
	v_mov_b32_e32 v15, v42
	v_mov_b32_e32 v16, v42
	v_mov_b32_e32 v17, v42
	v_mov_b32_e32 v34, v42
	v_mov_b32_e32 v35, v42
	v_mov_b32_e32 v36, v42
	v_mov_b32_e32 v37, v42
	v_mov_b32_e32 v10, v42
	v_mov_b32_e32 v11, v42
	v_mov_b32_e32 v12, v42
	v_mov_b32_e32 v13, v42
	v_mov_b32_e32 v38, v42
	v_mov_b32_e32 v39, v42
	v_mov_b32_e32 v40, v42
	v_mov_b32_e32 v41, v42
	v_mov_b32_e32 v2, v42
	v_mov_b32_e32 v3, v42
	v_mov_b32_e32 v4, v42
	v_mov_b32_e32 v5, v42
	v_mov_b32_e32 v18, v42
	v_mov_b32_e32 v19, v42
	v_mov_b32_e32 v20, v42
	v_mov_b32_e32 v21, v42
	v_mov_b32_e32 v6, v42
	v_mov_b32_e32 v7, v42
	v_mov_b32_e32 v8, v42
	v_mov_b32_e32 v9, v42
	v_mov_b32_e32 v22, v42
	v_mov_b32_e32 v23, v42
	v_mov_b32_e32 v24, v42
	v_mov_b32_e32 v25, v42
	v_mov_b32_e32 v110, v42
	v_mov_b32_e32 v111, v42
	v_mov_b32_e32 v112, v42
	v_mov_b32_e32 v113, v42
	v_mov_b32_e32 v118, v42
	v_mov_b32_e32 v119, v42
	v_mov_b32_e32 v120, v42
	v_mov_b32_e32 v121, v42
	v_mov_b32_e32 v106, v42
	v_mov_b32_e32 v107, v42
	v_mov_b32_e32 v108, v42
	v_mov_b32_e32 v109, v42
	v_mov_b32_e32 v122, v42
	v_mov_b32_e32 v123, v42
	v_mov_b32_e32 v124, v42
	v_mov_b32_e32 v125, v42
	v_mov_b32_e32 v82, v42
	v_mov_b32_e32 v83, v42
	v_mov_b32_e32 v84, v42
	v_mov_b32_e32 v85, v42
	v_mov_b32_e32 v114, v42
	v_mov_b32_e32 v115, v42
	v_mov_b32_e32 v116, v42
	v_mov_b32_e32 v117, v42
	v_mov_b32_e32 v86, v42
	v_mov_b32_e32 v87, v42
	v_mov_b32_e32 v88, v42
	v_mov_b32_e32 v89, v42
	v_mov_b32_e32 v126, v42
	v_mov_b32_e32 v127, v42
	v_mov_b32_e32 v128, v42
	v_mov_b32_e32 v129, v42
	s_branch .LBB0_1153
